# attention K/V LDS-DMA: key columns 24..39 (shared by the two column-half windows) default cache policy, all other pieces nt
# speedup vs baseline: 1.0128x; 1.0128x over previous
; template <int KIND> __device__ __forceinline__ void attn_dma(unsigned dst, const bf16_t* src, const AttnUnit& u, int wid, int lane) {
;     const int np = u.nrows * 5;
;     const char* base = (const char*)(src + ((size_t)(u.b * NHEAD + u.h) * SEQ + u.krow_lo * 64 + 24 * u.jh) * HD);
; #pragma unroll
;     for (int it = 0; it < 10; ++it) {
;         const int pi = it * 8 + wid;
;         if (pi < np) {
;             const int w = (pi * 205) >> 10, p = pi - 5 * w, c = 8 * p + (lane >> 3);
;             const int sw = (KIND == 0) ? (((c >> 1) & 1) | (((c >> 3) & 3) << 1)) : ((((c >> 1) & 1) << 1) | (((c >> 3) & 1) << 2));
;             const int ch = (lane & 7) ^ sw;
;             const char* gp = base + (w * 64 + c) * (HD * 2) + ch * 16;
;             glds16(gp, (unsigned)__builtin_amdgcn_readfirstlane(dst + pi * 1024));
;         }
;     }
; }
.LBB0_263:
	s_cmp_eq_u32 s98, 2
	s_cbranch_scc1 .LBB0_336
	s_cmpk_gt_i32 s86, 0xff
	s_cbranch_scc1 .LBB0_336
	s_mov_b32 s100, 0
	s_cmp_ge_u32 s85, 5
	s_cselect_b32 s1, 5, 0
	s_sub_i32 s0, s85, s1
	s_cmp_ge_u32 s0, 3
	s_cselect_b32 s1, 0x1, 0
	s_or_b32 s100, s100, s1
	s_cmp_le_u32 s0, 1
	s_cselect_b32 s1, 0x10000, 0
	s_or_b32 s100, s100, s1
	s_add_i32 s0, s0, 3
	s_cmp_ge_u32 s0, 5
	s_cselect_b32 s1, 5, 0
	s_sub_i32 s0, s0, s1
	s_cmp_ge_u32 s0, 3
	s_cselect_b32 s1, 0x2, 0
	s_or_b32 s100, s100, s1
	s_cmp_le_u32 s0, 1
	s_cselect_b32 s1, 0x20000, 0
	s_or_b32 s100, s100, s1
	s_add_i32 s0, s0, 3
	s_cmp_ge_u32 s0, 5
	s_cselect_b32 s1, 5, 0
	s_sub_i32 s0, s0, s1
	s_cmp_ge_u32 s0, 3
	s_cselect_b32 s1, 0x4, 0
	s_or_b32 s100, s100, s1
	s_cmp_le_u32 s0, 1
	s_cselect_b32 s1, 0x40000, 0
	s_or_b32 s100, s100, s1
	s_add_i32 s0, s0, 3
	s_cmp_ge_u32 s0, 5
	s_cselect_b32 s1, 5, 0
	s_sub_i32 s0, s0, s1
	s_cmp_ge_u32 s0, 3
	s_cselect_b32 s1, 0x8, 0
	s_or_b32 s100, s100, s1
	s_cmp_le_u32 s0, 1
	s_cselect_b32 s1, 0x80000, 0
	s_or_b32 s100, s100, s1
	s_add_i32 s0, s0, 3
	s_cmp_ge_u32 s0, 5
	s_cselect_b32 s1, 5, 0
	s_sub_i32 s0, s0, s1
	s_cmp_ge_u32 s0, 3
	s_cselect_b32 s1, 0x10, 0
	s_or_b32 s100, s100, s1
	s_cmp_le_u32 s0, 1
	s_cselect_b32 s1, 0x100000, 0
	s_or_b32 s100, s100, s1
	s_add_i32 s0, s0, 3
	s_cmp_ge_u32 s0, 5
	s_cselect_b32 s1, 5, 0
	s_sub_i32 s0, s0, s1
	s_cmp_ge_u32 s0, 3
	s_cselect_b32 s1, 0x20, 0
	s_or_b32 s100, s100, s1
	s_cmp_le_u32 s0, 1
	s_cselect_b32 s1, 0x200000, 0
	s_or_b32 s100, s100, s1
	s_add_i32 s0, s0, 3
	s_cmp_ge_u32 s0, 5
	s_cselect_b32 s1, 5, 0
	s_sub_i32 s0, s0, s1
	s_cmp_ge_u32 s0, 3
	s_cselect_b32 s1, 0x40, 0
	s_or_b32 s100, s100, s1
	s_cmp_le_u32 s0, 1
	s_cselect_b32 s1, 0x400000, 0
	s_or_b32 s100, s100, s1
	s_add_i32 s0, s0, 3
	s_cmp_ge_u32 s0, 5
	s_cselect_b32 s1, 5, 0
	s_sub_i32 s0, s0, s1
	s_cmp_ge_u32 s0, 3
	s_cselect_b32 s1, 0x80, 0
	s_or_b32 s100, s100, s1
	s_cmp_le_u32 s0, 1
	s_cselect_b32 s1, 0x800000, 0
	s_or_b32 s100, s100, s1
	s_add_i32 s0, s0, 3
	s_cmp_ge_u32 s0, 5
	s_cselect_b32 s1, 5, 0
	s_sub_i32 s0, s0, s1
	s_cmp_ge_u32 s0, 3
	s_cselect_b32 s1, 0x100, 0
	s_or_b32 s100, s100, s1
	s_cmp_le_u32 s0, 1
	s_cselect_b32 s1, 0x1000000, 0
	s_or_b32 s100, s100, s1
	s_add_i32 s0, s0, 3
	s_cmp_ge_u32 s0, 5
	s_cselect_b32 s1, 5, 0
	s_sub_i32 s0, s0, s1
	s_cmp_ge_u32 s0, 3
	s_cselect_b32 s1, 0x200, 0
	s_or_b32 s100, s100, s1
	s_cmp_le_u32 s0, 1
	s_cselect_b32 s1, 0x2000000, 0
	s_or_b32 s100, s100, s1
	s_add_i32 s0, s0, 3
	s_cmp_ge_u32 s0, 5
	s_cselect_b32 s1, 5, 0
	s_sub_i32 s0, s0, s1
	s_add_u32 s22, s28, 0x12000000
	s_addc_u32 s23, s29, 0
	s_add_u32 s40, s28, 0xe000000
	s_addc_u32 s41, s29, 0
	s_and_b32 s0, s33, 0xffffffc0
	v_add_u32_e32 v99, s0, v166
	s_mul_i32 s0, s85, 0xcd
	s_lshr_b32 s1, s0, 10
	s_mul_i32 s4, s1, -5
	v_ashrrev_i32_e32 v2, 3, v166
	s_add_i32 s4, s4, s85
	v_lshl_add_u32 v4, s4, 3, v2
	s_add_i32 s4, s0, 0x668
	s_lshr_b32 s4, s4, 10
	s_add_i32 s43, s85, 8
	s_mul_i32 s5, s4, -5
	s_add_i32 s5, s5, s43
	v_lshl_add_u32 v5, s5, 3, v2
	s_add_i32 s5, s0, 0xcd0
	s_lshr_b32 s5, s5, 10
	s_add_i32 s48, s85, 16
	s_mul_i32 s6, s5, -5
	s_add_i32 s6, s6, s48
	v_lshl_add_u32 v6, s6, 3, v2
	s_add_i32 s6, s0, 0x1338
	v_lshrrev_b32_e32 v1, 2, v4
	s_lshr_b32 s6, s6, 10
	v_bfe_u32 v0, v2, 1, 1
	v_and_b32_e32 v3, 7, v166
	v_and_b32_e32 v1, 6, v1
	s_add_i32 s50, s85, 24
	s_mul_i32 s7, s6, -5
	v_bitop3_b32 v1, v1, v3, v0 bitop3:0x36
	s_add_i32 s7, s7, s50
	v_lshlrev_b32_e32 v102, 4, v1
	v_lshrrev_b32_e32 v1, 2, v5
	v_lshl_add_u32 v7, s7, 3, v2
	s_add_i32 s7, s0, 0x19a0
	v_and_b32_e32 v1, 6, v1
	s_lshr_b32 s7, s7, 10
	v_bitop3_b32 v1, v1, v3, v0 bitop3:0x36
	s_add_i32 s54, s85, 32
	s_mul_i32 s8, s7, -5
	v_lshlrev_b32_e32 v106, 4, v1
	v_lshrrev_b32_e32 v1, 2, v6
	s_add_i32 s8, s8, s54
	v_and_b32_e32 v1, 6, v1
	v_lshl_add_u32 v8, s8, 3, v2
	s_add_i32 s8, s0, 0x2008
	v_bitop3_b32 v1, v1, v3, v0 bitop3:0x36
	s_lshr_b32 s8, s8, 10
	v_lshlrev_b32_e32 v110, 4, v1
	v_lshrrev_b32_e32 v1, 2, v7
	s_add_i32 s64, s85, 40
	s_mul_i32 s9, s8, -5
	v_and_b32_e32 v1, 6, v1
	s_add_i32 s9, s9, s64
	v_bitop3_b32 v1, v1, v3, v0 bitop3:0x36
	v_lshl_add_u32 v9, s9, 3, v2
	s_add_i32 s9, s0, 0x2670
	v_lshlrev_b32_e32 v114, 4, v1
	v_lshrrev_b32_e32 v1, 2, v8
	s_lshr_b32 s9, s9, 10
	v_and_b32_e32 v1, 6, v1
	s_add_i32 s66, s85, 48
	s_mul_i32 s10, s9, -5
	v_bitop3_b32 v1, v1, v3, v0 bitop3:0x36
	s_add_i32 s10, s10, s66
	v_lshlrev_b32_e32 v118, 4, v1
	v_lshrrev_b32_e32 v1, 2, v9
	v_lshl_add_u32 v10, s10, 3, v2
	s_add_i32 s10, s0, 0x2cd8
	v_and_b32_e32 v1, 6, v1
	s_lshr_b32 s10, s10, 10
	v_bitop3_b32 v1, v1, v3, v0 bitop3:0x36
	s_add_i32 s68, s85, 56
	s_mul_i32 s11, s10, -5
	v_lshlrev_b32_e32 v122, 4, v1
	v_lshrrev_b32_e32 v1, 2, v10
	s_add_i32 s11, s11, s68
	v_and_b32_e32 v1, 6, v1
	v_lshl_add_u32 v11, s11, 3, v2
	s_add_i32 s11, s0, 0x3340
	v_bitop3_b32 v1, v1, v3, v0 bitop3:0x36
	s_lshr_b32 s11, s11, 10
	v_lshlrev_b32_e32 v126, 4, v1
	v_lshrrev_b32_e32 v1, 2, v11
	s_add_i32 s70, s85, 64
	s_mul_i32 s12, s11, -5
	v_and_b32_e32 v1, 6, v1
	s_add_i32 s12, s12, s70
	s_addk_i32 s0, 0x39a8
	v_bitop3_b32 v1, v1, v3, v0 bitop3:0x36
	v_lshl_add_u32 v12, s12, 3, v2
	s_lshr_b32 s0, s0, 10
	v_lshlrev_b32_e32 v130, 4, v1
	v_lshrrev_b32_e32 v1, 2, v12
	s_add_i32 s72, s85, 0x48
	s_mul_i32 s12, s0, -5
	v_and_b32_e32 v1, 6, v1
	s_add_i32 s12, s12, s72
	v_bitop3_b32 v1, v1, v3, v0 bitop3:0x36
	v_lshl_add_u32 v13, s12, 3, v2
	v_lshlrev_b32_e32 v134, 4, v1
	v_lshrrev_b32_e32 v1, 2, v13
	v_and_b32_e32 v1, 6, v1
	v_bitop3_b32 v0, v1, v3, v0 bitop3:0x36
	v_lshlrev_b32_e32 v138, 4, v0
	v_lshlrev_b32_e32 v0, 3, v169
; template <int KIND> __device__ __forceinline__ void attn_dma(unsigned dst, const bf16_t* src, const AttnUnit& u, int wid, int lane) {
;     ...
;             const int w = (pi * 205) >> 10, p = pi - 5 * w, c = 8 * p + (lane >> 3);
;             const int sw = (KIND == 0) ? (((c >> 1) & 1) | (((c >> 3) & 3) << 1)) : ((((c >> 1) & 1) << 1) | (((c >> 3) & 1) << 2));
;             const int ch = (lane & 7) ^ sw;
;             const char* gp = base + (w * 64 + c) * (HD * 2) + ch * 16;
;             glds16(gp, (unsigned)__builtin_amdgcn_readfirstlane(dst + pi * 1024));
; __device__ __forceinline__ void p2_attention(Frame& F, const bf16_t* Qg, const bf16_t* Kg, const bf16_t* Vg, bf16_t* MIX) {
;     ...
;                 const int o = 8 * jb, kcol0 = 24 * u.jh + o, cq = 32 * u.jh + 16 * jb + q;
;                 int cs = cq - 8; cs = cs < 0 ? 0 : cs; cs = cs > 48 ? 48 : cs;
;                 f32x4 sc[8][2];
;                 {
;                     const int fk = ((q >> 1) & 1) | (((jb + (q >> 2)) & 3) << 1), x0 = g ^ fk;
;                     const LAS unsigned char* ka = lds + AT_A + (wbase * 40 + o + 8 * (q >> 2) + (q & 3)) * 128;
;                     const LAS unsigned char* k0p = ka + x0 * 16;
;                     const LAS unsigned char* k1p = ka + (x0 ^ 4) * 16;
; #pragma unroll
;                     for (int wl = 0; wl < 8; ++wl)
; #pragma unroll
;                         for (int blk = 0; blk < 2; ++blk) {
;                             const bf16x8 k0 = *(const LAS bf16x8*)(k0p + wl * 5120 + blk * 512), k1 = *(const LAS bf16x8*)(k1p + wl * 5120 + blk * 512);
;                             f32x4 a = (f32x4){0.f, 0.f, 0.f, 0.f};
;                             a = __builtin_amdgcn_mfma_f32_16x16x32_bf16(k0, qf[jb][0], a, 0, 0, 0);
;                             a = __builtin_amdgcn_mfma_f32_16x16x32_bf16(k1, qf[jb][1], a, 0, 0, 0);
;                             sc[wl][blk] = a;
;                         }
;                 }
;                 const LAS float* tab = (const LAS float*)(lds + AT_TAB) + (rs - r + 7) * 64 + 16 + (kcol0 - cq + 15) + 8 * g;
;                 const int voff = kcol0 + 8 * g - cs;
;                 float mx = -INFINITY;
; #pragma unroll
;                 for (int wl = 0; wl < 8; ++wl)
; #pragma unroll
;                     for (int blk = 0; blk < 2; ++blk)
; #pragma unroll
;                         for (int e = 0; e < 4; ++e) {
	v_ashrrev_i32_e32 v1, 31, v0
	v_lshl_add_u64 v[140:141], v[0:1], 1, s[36:37]
	v_and_b32_e32 v1, 2, v2
	v_lshrrev_b32_e32 v2, 1, v4
	v_and_b32_e32 v2, 4, v2
	v_bitop3_b32 v2, v2, v3, v1 bitop3:0x36
	v_lshlrev_b32_e32 v142, 4, v2
	v_lshrrev_b32_e32 v2, 1, v5
	v_and_b32_e32 v2, 4, v2
	v_bitop3_b32 v2, v2, v3, v1 bitop3:0x36
	v_lshlrev_b32_e32 v144, 4, v2
	v_lshrrev_b32_e32 v2, 1, v6
	v_and_b32_e32 v2, 4, v2
	v_bitop3_b32 v2, v2, v3, v1 bitop3:0x36
	v_lshlrev_b32_e32 v146, 4, v2
	v_lshrrev_b32_e32 v2, 1, v7
	v_and_b32_e32 v2, 4, v2
	v_bitop3_b32 v2, v2, v3, v1 bitop3:0x36
	v_lshlrev_b32_e32 v148, 4, v2
	v_lshrrev_b32_e32 v2, 1, v8
	v_and_b32_e32 v2, 4, v2
	v_bitop3_b32 v2, v2, v3, v1 bitop3:0x36
	v_lshlrev_b32_e32 v150, 4, v2
	v_lshrrev_b32_e32 v2, 1, v9
	v_and_b32_e32 v2, 4, v2
	v_bitop3_b32 v2, v2, v3, v1 bitop3:0x36
	v_lshlrev_b32_e32 v152, 4, v2
	v_lshrrev_b32_e32 v2, 1, v10
	v_and_b32_e32 v2, 4, v2
	v_bitop3_b32 v2, v2, v3, v1 bitop3:0x36
	v_lshlrev_b32_e32 v154, 4, v2
	v_lshrrev_b32_e32 v2, 1, v11
	v_and_b32_e32 v2, 4, v2
	v_bitop3_b32 v2, v2, v3, v1 bitop3:0x36
	v_lshlrev_b32_e32 v156, 4, v2
	v_lshrrev_b32_e32 v2, 1, v12
	v_and_b32_e32 v2, 4, v2
	v_bitop3_b32 v2, v2, v3, v1 bitop3:0x36
	v_lshlrev_b32_e32 v158, 4, v2
	v_lshrrev_b32_e32 v2, 1, v13
	v_and_b32_e32 v2, 4, v2
	v_bitop3_b32 v1, v2, v3, v1 bitop3:0x36
	s_lshl_b32 s4, s4, 13
	v_lshlrev_b32_e32 v160, 4, v1
	v_bfe_u32 v164, v166, 2, 2
	v_and_b32_e32 v1, 3, v166
	v_add_u32_e32 v170, 8, v0
	v_lshrrev_b32_e32 v0, 2, v166
	v_lshl_add_u32 v104, v5, 7, s4
	s_lshl_b32 s5, s5, 13
	s_add_i32 s12, 0, 0x12c00
	v_lshl_or_b32 v165, v164, 3, v1
	v_and_b32_e32 v5, 2, v0
	v_and_b32_e32 v0, 16, v96
	v_and_b32_e32 v1, 8, v96
	v_lshl_add_u32 v108, v6, 7, s5
	v_add3_u32 v6, s12, v0, v1
	v_lshlrev_b32_e32 v0, 6, v166
	v_mov_b32_e32 v97, 0
	v_and_b32_e32 v96, 0x3c0, v0
	v_and_b32_e32 v2, -16, v166
	s_lshl_b32 s1, s1, 13
	v_lshl_add_u64 v[0:1], s[24:25], 0, v[96:97]
	v_ashrrev_i32_e32 v3, 31, v2
	v_lshl_add_u32 v100, v4, 7, s1
	v_bfe_u32 v4, v166, 1, 1
	v_lshl_add_u64 v[162:163], v[0:1], 0, v[2:3]
	v_lshlrev_b32_e32 v0, 1, v164
	v_bitop3_b32 v1, v0, v169, v4 bitop3:0x36
	v_add_u32_e32 v0, 2, v0
	v_and_b32_e32 v0, 6, v0
	v_bitop3_b32 v0, v0, v169, v4 bitop3:0x36
	v_lshlrev_b32_e32 v173, 4, v0
	v_lshlrev_b32_e32 v0, 2, v169
	v_and_or_b32 v0, v0, 4, v5
	v_lshlrev_b32_e32 v176, 4, v0
	v_add_u32_e32 v0, 1, v169
	v_lshlrev_b32_e32 v171, 4, v1
	v_lshlrev_b32_e32 v1, 2, v0
	v_and_or_b32 v1, v1, 4, v5
	v_and_b32_e32 v185, 63, v166
	s_lshl_b32 s4, s43, 10
	s_lshl_b32 s5, s48, 10
	v_lshl_add_u32 v180, v0, 10, v6
	v_lshlrev_b32_e32 v181, 4, v1
	v_add_u32_e32 v0, -16, v185
	v_and_b32_e32 v1, 64, v168
	s_add_i32 s45, s4, 0
	s_add_i32 s49, s5, 0
	s_lshl_b32 s0, s0, 13
	s_add_i32 s37, s4, s12
	s_add_i32 s74, s5, s12
	v_cmp_gt_u32_e64 s[4:5], 31, v0
	v_xor_b32_e32 v0, 16, v168
	v_add_u32_e32 v1, 64, v1
	v_lshl_add_u32 v136, v13, 7, s0
	s_lshl_b32 s0, s72, 10
	v_cmp_lt_i32_e32 vcc, v0, v1
	s_lshl_b32 s1, s85, 10
	s_add_i32 s73, s0, 0
	s_add_i32 s81, s0, s12
	s_movk_i32 s0, 0x3c0
	v_cndmask_b32_e32 v0, v168, v0, vcc
	s_add_i32 s42, s1, 0
	s_add_i32 s36, s1, s12
	v_cmp_gt_i32_e64 s[20:21], s0, v99
	v_lshlrev_b32_e32 v186, 2, v0
	v_xor_b32_e32 v0, 32, v168
	s_add_i32 s0, 0, 0x25800
	s_lshl_b32 s1, s85, 8
	s_lshl_b32 s6, s6, 13
	s_lshl_b32 s7, s7, 13
	s_lshl_b32 s8, s8, 13
	s_lshl_b32 s9, s9, 13
	s_lshl_b32 s10, s10, 13
	s_lshl_b32 s11, s11, 13
	v_lshl_add_u32 v175, v169, 10, v6
	v_cmp_lt_i32_e32 vcc, v0, v1
	v_lshl_add_u32 v169, v169, 5, s0
	s_add_i32 s0, s0, s1
	v_and_b32_e32 v98, 15, v166
	v_lshl_add_u32 v112, v7, 7, s6
	s_lshl_b32 s6, s50, 10
	v_lshl_add_u32 v116, v8, 7, s7
	s_lshl_b32 s7, s54, 10
	v_lshl_add_u32 v120, v9, 7, s8
	s_lshl_b32 s8, s64, 10
	v_lshl_add_u32 v124, v10, 7, s9
	s_lshl_b32 s9, s66, 10
	v_lshl_add_u32 v128, v11, 7, s10
	s_lshl_b32 s10, s68, 10
	v_lshl_add_u32 v132, v12, 7, s11
	s_lshl_b32 s11, s70, 10
	v_cndmask_b32_e32 v0, v168, v0, vcc
	v_lshl_add_u32 v166, v166, 2, s0
	s_lshl_b32 s0, s86, 5
	v_ashrrev_i32_e32 v101, 31, v100
	v_mov_b32_e32 v103, v97
	v_ashrrev_i32_e32 v105, 31, v104
	v_mov_b32_e32 v107, v97
	v_ashrrev_i32_e32 v109, 31, v108
	v_mov_b32_e32 v111, v97
	v_ashrrev_i32_e32 v113, 31, v112
	v_mov_b32_e32 v115, v97
	s_add_i32 s51, s6, 0
	v_ashrrev_i32_e32 v117, 31, v116
	v_mov_b32_e32 v119, v97
	s_add_i32 s55, s7, 0
	v_ashrrev_i32_e32 v121, 31, v120
	v_mov_b32_e32 v123, v97
	s_add_i32 s65, s8, 0
	v_ashrrev_i32_e32 v125, 31, v124
	v_mov_b32_e32 v127, v97
	s_add_i32 s67, s9, 0
	v_ashrrev_i32_e32 v129, 31, v128
	v_mov_b32_e32 v131, v97
	s_add_i32 s69, s10, 0
	v_ashrrev_i32_e32 v133, 31, v132
	v_mov_b32_e32 v135, v97
	s_add_i32 s71, s11, 0
	v_ashrrev_i32_e32 v137, 31, v136
	v_mov_b32_e32 v139, v97
	v_mov_b32_e32 v143, v97
	v_mov_b32_e32 v145, v97
	v_mov_b32_e32 v147, v97
	v_mov_b32_e32 v149, v97
	s_add_i32 s75, s6, s12
	v_mov_b32_e32 v151, v97
	s_add_i32 s76, s7, s12
	v_mov_b32_e32 v153, v97
	s_add_i32 s77, s8, s12
	v_mov_b32_e32 v155, v97
	s_add_i32 s78, s9, s12
	v_mov_b32_e32 v157, v97
	s_add_i32 s79, s10, s12
	v_mov_b32_e32 v159, v97
	s_add_i32 s80, s11, s12
	v_mov_b32_e32 v161, v97
	v_xor_b32_e32 v172, 64, v171
	v_xor_b32_e32 v174, 64, v173
	v_xor_b32_e32 v177, 32, v176
	v_xor_b32_e32 v178, 64, v176
	v_xor_b32_e32 v179, 0x60, v176
	v_xor_b32_e32 v182, 32, v181
	v_xor_b32_e32 v183, 64, v181
	v_xor_b32_e32 v184, 0x60, v181
	s_lshl_b32 s82, s3, 3
	v_lshlrev_b32_e32 v168, 2, v0
	s_or_b32 s83, s0, 4
	s_lshl_b32 s86, s3, 5
	s_movk_i32 s87, 0x1bf
	s_mov_b32 s88, 0xff800000
	v_mov_b32_e32 v187, 0xff800000
	s_branch .LBB0_266

; __device__ __forceinline__ AttnUnit attn_decode(int un) {
;     AttnUnit u; const int bh = un >> 4, rc = (un >> 1) & 7; u.jh = un & 1; u.b = bh >> 3; u.h = bh & 7;
;     u.r0 = 8 * rc; u.krow_lo = rs_of(u.r0); u.nrows = rs_of(u.r0 + 7) + 8 - u.krow_lo;
;     return u;
; }
; __device__ __forceinline__ void glds16(const void* gsrc, unsigned lds_dst) { unsigned keep;
;     asm volatile("s_mov_b32 %0, m0\n\ts_mov_b32 m0, %2\n\ts_nop 0\n\tglobal_load_lds_dwordx4 %1, off\n\ts_mov_b32 m0, %0" : "=&s"(keep) : "v"(gsrc), "s"(lds_dst) : "memory"); }
; template <int KIND> __device__ __forceinline__ void attn_dma(unsigned dst, const bf16_t* src, const AttnUnit& u, int wid, int lane) {
;     const int np = u.nrows * 5;
;     const char* base = (const char*)(src + ((size_t)(u.b * NHEAD + u.h) * SEQ + u.krow_lo * 64 + 24 * u.jh) * HD);
; #pragma unroll
;     for (int it = 0; it < 10; ++it) {
;         const int pi = it * 8 + wid;
;         if (pi < np) {
;             const int w = (pi * 205) >> 10, p = pi - 5 * w, c = 8 * p + (lane >> 3);
; __device__ __forceinline__ void p2_attention(Frame& F, const bf16_t* Qg, const bf16_t* Kg, const bf16_t* Vg, bf16_t* MIX) {
;     ...
;         AttnUnit u = attn_decode(uidx);
;         attn_dma<0>(lds0 + AT_A, Kg, u, wid, lane);
.LBB0_271:
	s_or_b64 exec, exec, s[6:7]
	s_ashr_i32 s92, s44, 7
	s_lshl_b32 s0, s44, 2
	s_and_b32 s90, s0, 32
	s_lshl_b32 s6, s92, 3
	v_sub_u32_e64 v188, s90, 4 clamp
	s_or_b32 s6, s6, s89
	s_or_b32 s0, s90, 11
	v_readfirstlane_b32 s1, v188
	s_ashr_i32 s7, s6, 31
	s_sub_i32 s91, s0, s1
	s_lshl_b64 s[6:7], s[6:7], 12
	s_lshl_b32 s1, s1, 6
	s_or_b32 s8, s6, s1
	s_mov_b32 s9, s7
	s_lshl_b64 s[8:9], s[8:9], 7
	s_add_u32 s8, s40, s8
	s_mul_i32 s0, s91, 5
	s_addc_u32 s9, s41, s9
	s_mov_b32 s101, s100
	s_cmp_ge_i32 s85, s0
	s_cbranch_scc0 .LBB0_327
	s_cmp_ge_i32 s43, s0
	s_cbranch_scc0 .LBB0_328

; __device__ __forceinline__ void glds16(const void* gsrc, unsigned lds_dst) { unsigned keep;
;     asm volatile("s_mov_b32 %0, m0\n\ts_mov_b32 m0, %2\n\ts_nop 0\n\tglobal_load_lds_dwordx4 %1, off\n\ts_mov_b32 m0, %0" : "=&s"(keep) : "v"(gsrc), "s"(lds_dst) : "memory"); }
; template <int KIND> __device__ __forceinline__ void attn_dma(unsigned dst, const bf16_t* src, const AttnUnit& u, int wid, int lane) {
;     const int np = u.nrows * 5;
;     const char* base = (const char*)(src + ((size_t)(u.b * NHEAD + u.h) * SEQ + u.krow_lo * 64 + 24 * u.jh) * HD);
; #pragma unroll
;     for (int it = 0; it < 10; ++it) {
;         const int pi = it * 8 + wid;
;         if (pi < np) {
;             const int w = (pi * 205) >> 10, p = pi - 5 * w, c = 8 * p + (lane >> 3);
;             const int sw = (KIND == 0) ? (((c >> 1) & 1) | (((c >> 3) & 3) << 1)) : ((((c >> 1) & 1) << 1) | (((c >> 3) & 1) << 2));
;             const int ch = (lane & 7) ^ sw;
;             const char* gp = base + (w * 64 + c) * (HD * 2) + ch * 16;
;             glds16(gp, (unsigned)__builtin_amdgcn_readfirstlane(dst + pi * 1024));
.LBB0_281:
	s_waitcnt vmcnt(5)
	v_lshl_add_u64 v[0:1], s[8:9], 0, v[136:137]
	v_lshl_add_u64 v[0:1], v[0:1], 0, v[138:139]
	s_mov_b32 s0, m0
	s_mov_b32 m0, s73
	s_nop 0
	s_bitcmp1_b32 s101, 9
	s_cbranch_scc1 .Latt_def_ik9
	global_load_lds_dwordx4 v[0:1], off nt
	s_branch .Latt_done_ik9
.Latt_def_ik9:
	global_load_lds_dwordx4 v[0:1], off
.Latt_done_ik9:
	s_mov_b32 m0, s0

; template <int KIND> __device__ __forceinline__ void attn_dma(unsigned dst, const bf16_t* src, const AttnUnit& u, int wid, int lane) {
;     const int np = u.nrows * 5;
;     const char* base = (const char*)(src + ((size_t)(u.b * NHEAD + u.h) * SEQ + u.krow_lo * 64 + 24 * u.jh) * HD);
; #pragma unroll
;     for (int it = 0; it < 10; ++it) {
;         const int pi = it * 8 + wid;
;         if (pi < np) {
; __device__ __forceinline__ void p2_attention(Frame& F, const bf16_t* Qg, const bf16_t* Kg, const bf16_t* Vg, bf16_t* MIX) {
;     ...
;             attn_dma<1>(lds0 + AT_B, Vg, u, wid, lane);
.LBB0_285:
	s_lshl_b32 s0, s92, 3
	s_or_b32 s6, s0, s89
	s_ashr_i32 s7, s6, 31
	s_lshl_b64 s[6:7], s[6:7], 12
	v_lshlrev_b32_e32 v96, 6, v188
	v_lshl_add_u64 v[16:17], s[6:7], 0, v[96:97]
	s_mul_i32 s0, s95, 24
	v_or_b32_e32 v16, s0, v16
	s_mul_i32 s1, s91, 5
	v_lshlrev_b64 v[16:17], 7, v[16:17]
	s_lshl_b32 s101, s95, 4
	s_lshr_b32 s101, s100, s101
	s_cmp_ge_i32 s85, s1
	v_lshl_add_u64 v[16:17], s[22:23], 0, v[16:17]
	s_waitcnt vmcnt(2)
	s_cbranch_scc0 .LBB0_307
	s_cmp_ge_i32 s43, s1
	s_cbranch_scc0 .LBB0_308

; #define LAS __attribute__((address_space(3)))
; __device__ __forceinline__ void p2_attention(Frame& F, const bf16_t* Qg, const bf16_t* Kg, const bf16_t* Vg, bf16_t* MIX) {
;     ...
;             const int r = u.r0 + wid, rs = rs_of(r), wbase = rs - u.krow_lo;
;             u32x4 pw[2][8]; float il[2];
; #pragma unroll
;             for (int jb = 0; jb < 2; ++jb) {
;                 const int o = 8 * jb, kcol0 = 24 * u.jh + o, cq = 32 * u.jh + 16 * jb + q;
;                 int cs = cq - 8; cs = cs < 0 ? 0 : cs; cs = cs > 48 ? 48 : cs;
;                 f32x4 sc[8][2];
;                 {
;                     const int fk = ((q >> 1) & 1) | (((jb + (q >> 2)) & 3) << 1), x0 = g ^ fk;
;                     const LAS unsigned char* ka = lds + AT_A + (wbase * 40 + o + 8 * (q >> 2) + (q & 3)) * 128;
;                     const LAS unsigned char* k0p = ka + x0 * 16;
;                     const LAS unsigned char* k1p = ka + (x0 ^ 4) * 16;
; #pragma unroll
;                     for (int wl = 0; wl < 8; ++wl)
; #pragma unroll
;                         for (int blk = 0; blk < 2; ++blk) {
;                             const bf16x8 k0 = *(const LAS bf16x8*)(k0p + wl * 5120 + blk * 512), k1 = *(const LAS bf16x8*)(k1p + wl * 5120 + blk * 512);
;                             f32x4 a = (f32x4){0.f, 0.f, 0.f, 0.f};
;                             a = __builtin_amdgcn_mfma_f32_16x16x32_bf16(k0, qf[jb][0], a, 0, 0, 0);
;                             a = __builtin_amdgcn_mfma_f32_16x16x32_bf16(k1, qf[jb][1], a, 0, 0, 0);
;                             sc[wl][blk] = a;
;                         }
;                 }
;                 const LAS float* tab = (const LAS float*)(lds + AT_TAB) + (rs - r + 7) * 64 + 16 + (kcol0 - cq + 15) + 8 * g;
;                 const int voff = kcol0 + 8 * g - cs;
;                 float mx = -INFINITY;
; #pragma unroll
;                 for (int wl = 0; wl < 8; ++wl)
; #pragma unroll
;                     for (int blk = 0; blk < 2; ++blk)
; #pragma unroll
;                         for (int e = 0; e < 4; ++e) {
;                             const int ep = 4 * blk + e;
;                             float s_ = sc[wl][blk][e] + tab[wl * 64 + ep];
;                             s_ = ((unsigned)(voff + ep) < 16u) ? s_ : -INFINITY;
;                             sc[wl][blk][e] = s_; mx = fmaxf(mx, s_);
.LBB0_295:
	v_lshl_add_u64 v[16:17], v[16:17], 0, v[136:137]
	v_lshl_add_u64 v[16:17], v[16:17], 0, v[160:161]
	s_mov_b32 s1, m0
	s_mov_b32 m0, s81
	s_nop 0
	s_bitcmp1_b32 s101, 9
	s_cbranch_scc1 .Latt_def_v9
	global_load_lds_dwordx4 v[16:17], off nt
	s_branch .Latt_done_v9
.Latt_def_v9:
	global_load_lds_dwordx4 v[16:17], off
.Latt_done_v9:
	s_mov_b32 m0, s1
.LBB0_296:
	s_add_i32 s96, s90, s85
	v_med3_i32 v16, s96, 4, 60
	v_add_u32_e32 v54, -4, v16
	v_sub_u32_e32 v16, v54, v188
	v_mul_lo_u32 v96, v16, 40
	v_add_u32_e32 v16, v165, v96
	v_lshl_add_u32 v49, v16, 7, 0
	v_add_u32_e32 v94, v49, v171
	v_add_u32_e32 v95, v49, v172
	ds_read_b128 v[16:19], v94
	ds_read_b128 v[20:23], v94 offset:512
	ds_read_b128 v[24:27], v94 offset:5120
	ds_read_b128 v[28:31], v95
	ds_read_b128 v[32:35], v94 offset:5632
	ds_read_b128 v[36:39], v95 offset:512
	s_waitcnt lgkmcnt(5)
	v_mfma_f32_16x16x32_bf16 v[16:19], v[16:19], v[0:3], 0
	s_lshl_b32 s97, s95, 5
	v_or_b32_e32 v48, s97, v98
	v_max_i32_e32 v191, 8, v48
	s_waitcnt lgkmcnt(4)
	v_mfma_f32_16x16x32_bf16 v[20:23], v[20:23], v[0:3], 0
	v_add_u32_e32 v190, s0, v170
	v_sub_u32_e32 v191, v190, v191
	v_cmp_gt_u32_e32 vcc, 16, v191
	s_waitcnt lgkmcnt(3)
	v_mfma_f32_16x16x32_bf16 v[24:27], v[24:27], v[0:3], 0
	v_add_u32_e32 v251, v49, v173
	v_add_u32_e32 v49, v49, v174
	s_cmp_eq_u32 s93, -1
	s_waitcnt lgkmcnt(2)
	v_mfma_f32_16x16x32_bf16 v[16:19], v[28:31], v[4:7], v[16:19]
	s_waitcnt lgkmcnt(0)
	v_mfma_f32_16x16x32_bf16 v[20:23], v[36:39], v[4:7], v[20:23]
	ds_read_b128 v[28:31], v95 offset:5120
	ds_read_b128 v[36:39], v95 offset:5632
	s_waitcnt lgkmcnt(1)
	v_mfma_f32_16x16x32_bf16 v[40:43], v[28:31], v[4:7], v[24:27]
	ds_read_b128 v[28:31], v94 offset:10240
	v_mfma_f32_16x16x32_bf16 v[24:27], v[32:35], v[0:3], 0
	s_waitcnt lgkmcnt(1)
	v_mfma_f32_16x16x32_bf16 v[36:39], v[36:39], v[4:7], v[24:27]
	s_nop 5
	ds_read_b128 v[24:27], v95 offset:10240
	ds_read_b128 v[32:35], v94 offset:10752
	ds_read_b128 v[44:47], v95 offset:10752
	s_waitcnt lgkmcnt(3)
	v_mfma_f32_16x16x32_bf16 v[28:31], v[28:31], v[0:3], 0
	s_waitcnt lgkmcnt(2)
	v_mfma_f32_16x16x32_bf16 v[50:53], v[24:27], v[4:7], v[28:31]
	v_subrev_u32_e32 v24, s96, v54
	v_lshl_add_u32 v189, v24, 8, v169
	s_waitcnt lgkmcnt(1)
	v_mfma_f32_16x16x32_bf16 v[24:27], v[32:35], v[0:3], 0
	s_nop 1
	ds_read_b128 v[28:31], v94 offset:15360
	ds_read_b128 v[32:35], v94 offset:15872
	ds_read_b128 v[54:57], v95 offset:15360
	ds_read_b128 v[58:61], v95 offset:15872
	s_waitcnt lgkmcnt(2)
	v_mfma_f32_16x16x32_bf16 v[32:35], v[32:35], v[0:3], 0
	v_mfma_f32_16x16x32_bf16 v[44:47], v[44:47], v[4:7], v[24:27]
	s_nop 2
	ds_read_b128 v[24:27], v94 offset:20480
	ds_read_b128 v[62:65], v94 offset:20992
	ds_read_b128 v[66:69], v95 offset:20480
	ds_read_b128 v[70:73], v95 offset:20992
	ds_read_b128 v[74:77], v94 offset:25600
	ds_read_b128 v[78:81], v94 offset:26112
	ds_read_b128 v[82:85], v95 offset:25600
	ds_read_b128 v[86:89], v95 offset:26112
	v_mfma_f32_16x16x32_bf16 v[28:31], v[28:31], v[0:3], 0
	s_waitcnt lgkmcnt(8)
	v_mfma_f32_16x16x32_bf16 v[58:61], v[58:61], v[4:7], v[32:35]
	s_nop 2
	v_sub_u32_e32 v32, s0, v48
	s_waitcnt lgkmcnt(7)
	v_mfma_f32_16x16x32_bf16 v[24:27], v[24:27], v[0:3], 0
	v_lshl_add_u32 v218, v32, 2, v189
	v_add_u32_e32 v32, 0x77c, v218
	v_add_u32_e32 v34, 0x784, v218
	v_mfma_f32_16x16x32_bf16 v[54:57], v[54:57], v[4:7], v[28:31]
	s_nop 2
	ds_read_b128 v[28:31], v94 offset:30720
	ds_read_b128 v[90:93], v94 offset:31232
	ds_read_b128 v[192:195], v95 offset:30720
	ds_read_b128 v[196:199], v95 offset:31232
	ds_read_b128 v[200:203], v94 offset:35840
	ds_read_b128 v[204:207], v94 offset:36352
	ds_read_b128 v[208:211], v95 offset:35840
	ds_read_b128 v[212:215], v95 offset:36352
	ds_read2_b32 v[32:33], v32 offset1:1
	s_waitcnt lgkmcnt(14)
	v_mfma_f32_16x16x32_bf16 v[66:69], v[66:69], v[4:7], v[24:27]
	v_add_u32_e32 v94, 0x78c, v218
	v_add_u32_e32 v216, 0x794, v218
	ds_read2_b32 v[34:35], v34 offset1:1
	ds_read2_b32 v[94:95], v94 offset1:1
	ds_read2_b32 v[216:217], v216 offset1:1
	v_mfma_f32_16x16x32_bf16 v[24:27], v[62:65], v[0:3], 0
	s_waitcnt lgkmcnt(3)
	v_add_f32_e32 v16, v16, v32
	v_cndmask_b32_e32 v219, v187, v16, vcc
	v_add_f32_e32 v16, v17, v33
	v_mfma_f32_16x16x32_bf16 v[62:65], v[70:73], v[4:7], v[24:27]
	v_add_u32_e32 v17, 1, v191
	v_cmp_gt_u32_e64 s[6:7], 16, v17
	v_add_u32_e32 v17, 2, v191
	v_mfma_f32_16x16x32_bf16 v[24:27], v[74:77], v[0:3], 0
	v_cndmask_b32_e64 v220, v187, v16, s[6:7]
	s_waitcnt lgkmcnt(2)
	v_add_f32_e32 v16, v18, v34
	v_cmp_gt_u32_e64 s[8:9], 16, v17
	v_add_u32_e32 v17, 3, v191
	v_mfma_f32_16x16x32_bf16 v[70:73], v[82:85], v[4:7], v[24:27]
	v_cndmask_b32_e64 v82, v187, v16, s[8:9]
	v_add_f32_e32 v16, v19, v35
	v_cmp_gt_u32_e64 s[10:11], 16, v17
	v_mfma_f32_16x16x32_bf16 v[24:27], v[78:81], v[0:3], 0
	s_waitcnt lgkmcnt(1)
	v_add_f32_e32 v20, v20, v94
	v_cndmask_b32_e64 v83, v187, v16, s[10:11]
	v_max3_f32 v74, v219, s88, v220
	v_mfma_f32_16x16x32_bf16 v[16:19], v[28:31], v[0:3], 0
	s_waitcnt lgkmcnt(0)
; #define LAS __attribute__((address_space(3)))
; __device__ __forceinline__ void p2_attention(Frame& F, const bf16_t* Qg, const bf16_t* Kg, const bf16_t* Vg, bf16_t* MIX) {
;     ...
;                 const LAS float* tab = (const LAS float*)(lds + AT_TAB) + (rs - r + 7) * 64 + 16 + (kcol0 - cq + 15) + 8 * g;
;                 const int voff = kcol0 + 8 * g - cs;
;                 float mx = -INFINITY;
; #pragma unroll
;                 for (int wl = 0; wl < 8; ++wl)
; #pragma unroll
;                     for (int blk = 0; blk < 2; ++blk)
; #pragma unroll
;                         for (int e = 0; e < 4; ++e) {
;                             const int ep = 4 * blk + e;
;                             float s_ = sc[wl][blk][e] + tab[wl * 64 + ep];
;                             s_ = ((unsigned)(voff + ep) < 16u) ? s_ : -INFINITY;
;                             sc[wl][blk][e] = s_; mx = fmaxf(mx, s_);
;                         }
;                 mx = fmaxf(mx, __shfl_xor(mx, 16)); mx = fmaxf(mx, __shfl_xor(mx, 32));
	v_add_f32_e32 v75, v23, v217
	v_max3_f32 v74, v74, v82, v83
	v_add_u32_e32 v76, 0x884, v218
	v_mfma_f32_16x16x32_bf16 v[28:31], v[192:195], v[4:7], v[16:19]
	v_add_u32_e32 v78, 0x88c, v218
	v_add_u32_e32 v80, 0x894, v218
	v_mfma_f32_16x16x32_bf16 v[16:19], v[90:93], v[0:3], 0
	v_mfma_f32_16x16x32_bf16 v[32:35], v[86:89], v[4:7], v[24:27]
	s_nop 2
	v_add_u32_e32 v24, 4, v191
	v_cmp_gt_u32_e64 s[12:13], 16, v24
	v_mfma_f32_16x16x32_bf16 v[24:27], v[196:199], v[4:7], v[16:19]
	s_nop 0
	v_cndmask_b32_e64 v84, v187, v20, s[12:13]
	v_add_f32_e32 v20, v21, v95
	v_mfma_f32_16x16x32_bf16 v[16:19], v[200:203], v[0:3], 0
	v_add_u32_e32 v21, 5, v191
	v_cmp_gt_u32_e64 s[14:15], 16, v21
	v_add_u32_e32 v21, 6, v191
	v_cmp_gt_u32_e64 s[16:17], 16, v21
	v_cndmask_b32_e64 v85, v187, v20, s[14:15]
	v_add_f32_e32 v20, v22, v216
	v_cndmask_b32_e64 v86, v187, v20, s[16:17]
	v_mfma_f32_16x16x32_bf16 v[20:23], v[208:211], v[4:7], v[16:19]
	v_max3_f32 v74, v74, v84, v85
	s_nop 1
	v_add_u32_e32 v16, 7, v191
	v_cmp_gt_u32_e64 s[18:19], 16, v16
	v_mfma_f32_16x16x32_bf16 v[16:19], v[204:207], v[0:3], 0
	s_nop 0
	v_cndmask_b32_e64 v87, v187, v75, s[18:19]
	v_max3_f32 v88, v74, v86, v87
	v_add_u32_e32 v74, 0x87c, v218
	ds_read2_b32 v[74:75], v74 offset1:1
	ds_read2_b32 v[76:77], v76 offset1:1
	ds_read2_b32 v[78:79], v78 offset1:1
	ds_read2_b32 v[80:81], v80 offset1:1
	v_mfma_f32_16x16x32_bf16 v[16:19], v[212:215], v[4:7], v[16:19]
	s_waitcnt lgkmcnt(3)
	v_add_f32_e32 v40, v40, v74
	v_cndmask_b32_e32 v74, v187, v40, vcc
	v_add_f32_e32 v40, v41, v75
	s_waitcnt lgkmcnt(2)
	v_add_f32_e32 v41, v42, v76
	v_cndmask_b32_e64 v75, v187, v40, s[6:7]
	v_cndmask_b32_e64 v76, v187, v41, s[8:9]
	v_add_f32_e32 v41, v43, v77
	s_waitcnt lgkmcnt(1)
	v_add_f32_e32 v36, v36, v78
	v_max3_f32 v40, v88, v74, v75
	v_cndmask_b32_e64 v77, v187, v41, s[10:11]
	v_cndmask_b32_e64 v78, v187, v36, s[12:13]
	v_add_f32_e32 v36, v37, v79
	s_waitcnt lgkmcnt(0)
	v_add_f32_e32 v37, v38, v80
	v_max3_f32 v40, v40, v76, v77
	v_cndmask_b32_e64 v79, v187, v36, s[14:15]
	v_cndmask_b32_e64 v80, v187, v37, s[16:17]
	v_add_f32_e32 v37, v39, v81
	v_max3_f32 v36, v40, v78, v79
	v_cndmask_b32_e64 v81, v187, v37, s[18:19]
	v_max3_f32 v88, v36, v80, v81
	v_add_u32_e32 v36, 0x97c, v218
	ds_read2_b32 v[36:37], v36 offset1:1
	v_add_u32_e32 v38, 0x984, v218
	v_add_u32_e32 v40, 0x98c, v218
	v_add_u32_e32 v42, 0x994, v218
	ds_read2_b32 v[38:39], v38 offset1:1
	ds_read2_b32 v[40:41], v40 offset1:1
	ds_read2_b32 v[42:43], v42 offset1:1
	s_waitcnt lgkmcnt(3)
	v_add_f32_e32 v36, v50, v36
	v_cndmask_b32_e32 v50, v187, v36, vcc
	v_add_f32_e32 v36, v51, v37
	s_waitcnt lgkmcnt(2)
	v_add_f32_e32 v37, v52, v38
	v_cndmask_b32_e64 v52, v187, v37, s[8:9]
	v_add_f32_e32 v37, v53, v39
	v_cndmask_b32_e64 v53, v187, v37, s[10:11]
	s_waitcnt lgkmcnt(1)
	v_add_f32_e32 v37, v44, v40
	v_cndmask_b32_e64 v51, v187, v36, s[6:7]
	v_cndmask_b32_e64 v44, v187, v37, s[12:13]
	v_add_f32_e32 v37, v45, v41
	v_max3_f32 v36, v88, v50, v51
	v_cndmask_b32_e64 v45, v187, v37, s[14:15]
	s_waitcnt lgkmcnt(0)
	v_add_f32_e32 v37, v46, v42
	v_max3_f32 v36, v36, v52, v53
	v_cndmask_b32_e64 v46, v187, v37, s[16:17]
	v_add_f32_e32 v37, v47, v43
	v_max3_f32 v36, v36, v44, v45
	v_cndmask_b32_e64 v47, v187, v37, s[18:19]
	v_max3_f32 v88, v36, v46, v47
	v_add_u32_e32 v36, 0xa7c, v218
	ds_read2_b32 v[36:37], v36 offset1:1
	v_add_u32_e32 v38, 0xa84, v218
	v_add_u32_e32 v40, 0xa8c, v218
	v_add_u32_e32 v42, 0xa94, v218
	ds_read2_b32 v[38:39], v38 offset1:1
	ds_read2_b32 v[40:41], v40 offset1:1
	ds_read2_b32 v[42:43], v42 offset1:1
	s_waitcnt lgkmcnt(3)
	v_add_f32_e32 v36, v54, v36
	v_cndmask_b32_e32 v54, v187, v36, vcc
	v_add_f32_e32 v36, v55, v37
	s_waitcnt lgkmcnt(2)
	v_add_f32_e32 v37, v56, v38
	v_cndmask_b32_e64 v56, v187, v37, s[8:9]
	v_add_f32_e32 v37, v57, v39
	v_cndmask_b32_e64 v57, v187, v37, s[10:11]
	s_waitcnt lgkmcnt(1)
	v_add_f32_e32 v37, v58, v40
	v_cndmask_b32_e64 v55, v187, v36, s[6:7]
	v_cndmask_b32_e64 v58, v187, v37, s[12:13]
	v_add_f32_e32 v37, v59, v41
	v_max3_f32 v36, v88, v54, v55
	v_cndmask_b32_e64 v59, v187, v37, s[14:15]
	s_waitcnt lgkmcnt(0)
	v_add_f32_e32 v37, v60, v42
	v_max3_f32 v36, v36, v56, v57
	v_cndmask_b32_e64 v60, v187, v37, s[16:17]
	v_add_f32_e32 v37, v61, v43
	v_max3_f32 v36, v36, v58, v59
	v_cndmask_b32_e64 v61, v187, v37, s[18:19]
	v_max3_f32 v88, v36, v60, v61
	v_add_u32_e32 v36, 0xb7c, v218
	ds_read2_b32 v[36:37], v36 offset1:1
	v_add_u32_e32 v38, 0xb84, v218
	v_add_u32_e32 v40, 0xb8c, v218
	v_add_u32_e32 v42, 0xb94, v218
	ds_read2_b32 v[38:39], v38 offset1:1
	ds_read2_b32 v[40:41], v40 offset1:1
	ds_read2_b32 v[42:43], v42 offset1:1
	s_waitcnt lgkmcnt(3)
	v_add_f32_e32 v36, v66, v36
	v_cndmask_b32_e32 v66, v187, v36, vcc
	v_add_f32_e32 v36, v67, v37
	s_waitcnt lgkmcnt(2)
	v_add_f32_e32 v37, v68, v38
	v_cndmask_b32_e64 v68, v187, v37, s[8:9]
	v_add_f32_e32 v37, v69, v39
	v_cndmask_b32_e64 v69, v187, v37, s[10:11]
	s_waitcnt lgkmcnt(1)
	v_add_f32_e32 v37, v62, v40
	v_cndmask_b32_e64 v67, v187, v36, s[6:7]
	v_cndmask_b32_e64 v62, v187, v37, s[12:13]
	v_add_f32_e32 v37, v63, v41
	v_max3_f32 v36, v88, v66, v67
	v_cndmask_b32_e64 v63, v187, v37, s[14:15]
	s_waitcnt lgkmcnt(0)
	v_add_f32_e32 v37, v64, v42
	v_max3_f32 v36, v36, v68, v69
	v_cndmask_b32_e64 v64, v187, v37, s[16:17]
	v_add_f32_e32 v37, v65, v43
	v_max3_f32 v36, v36, v62, v63
	v_cndmask_b32_e64 v65, v187, v37, s[18:19]
	v_max3_f32 v88, v36, v64, v65
	v_add_u32_e32 v36, 0xc7c, v218
	ds_read2_b32 v[36:37], v36 offset1:1
	v_add_u32_e32 v38, 0xc84, v218
	v_add_u32_e32 v40, 0xc8c, v218
	v_add_u32_e32 v42, 0xc94, v218
	ds_read2_b32 v[38:39], v38 offset1:1
	ds_read2_b32 v[40:41], v40 offset1:1
	ds_read2_b32 v[42:43], v42 offset1:1
	s_waitcnt lgkmcnt(3)
; __device__ __forceinline__ unsigned cvt_pk_bf16(float lo, float hi) { unsigned r; asm volatile("v_cvt_pk_bf16_f32 %0, %1, %2" : "=v"(r) : "v"(lo), "v"(hi)); return r; }
; __device__ __forceinline__ void p2_attention(Frame& F, const bf16_t* Qg, const bf16_t* Kg, const bf16_t* Vg, bf16_t* MIX) {
;     ...
;                 float mx = -INFINITY;
; #pragma unroll
;                 for (int wl = 0; wl < 8; ++wl)
; #pragma unroll
;                     for (int blk = 0; blk < 2; ++blk)
; #pragma unroll
;                         for (int e = 0; e < 4; ++e) {
;                             const int ep = 4 * blk + e;
;                             float s_ = sc[wl][blk][e] + tab[wl * 64 + ep];
;                             s_ = ((unsigned)(voff + ep) < 16u) ? s_ : -INFINITY;
;                             sc[wl][blk][e] = s_; mx = fmaxf(mx, s_);
;                         }
;                 mx = fmaxf(mx, __shfl_xor(mx, 16)); mx = fmaxf(mx, __shfl_xor(mx, 32));
;                 float l = 0.f;
; #pragma unroll
;                 for (int wl = 0; wl < 8; ++wl) {
;                     float p[8];
; #pragma unroll
;                     for (int blk = 0; blk < 2; ++blk)
; #pragma unroll
;                         for (int e = 0; e < 4; ++e) { p[4 * blk + e] = __builtin_amdgcn_exp2f(sc[wl][blk][e] - mx); l += p[4 * blk + e]; }
;                     pw[jb][wl].x = cvt_pk_bf16(p[0], p[1]); pw[jb][wl].y = cvt_pk_bf16(p[2], p[3]); pw[jb][wl].z = cvt_pk_bf16(p[4], p[5]); pw[jb][wl].w = cvt_pk_bf16(p[6], p[7]);
	v_add_f32_e32 v36, v70, v36
	v_cndmask_b32_e32 v70, v187, v36, vcc
	v_add_f32_e32 v36, v71, v37
	s_waitcnt lgkmcnt(2)
	v_add_f32_e32 v37, v72, v38
	v_cndmask_b32_e64 v71, v187, v36, s[6:7]
	v_cndmask_b32_e64 v72, v187, v37, s[8:9]
	v_add_f32_e32 v37, v73, v39
	s_waitcnt lgkmcnt(1)
	v_add_f32_e32 v32, v32, v40
	v_max3_f32 v36, v88, v70, v71
	v_cndmask_b32_e64 v73, v187, v37, s[10:11]
	v_cndmask_b32_e64 v40, v187, v32, s[12:13]
	v_add_f32_e32 v32, v33, v41
	s_waitcnt lgkmcnt(0)
	v_add_f32_e32 v33, v34, v42
	v_max3_f32 v36, v36, v72, v73
	v_cndmask_b32_e64 v41, v187, v32, s[14:15]
	v_cndmask_b32_e64 v42, v187, v33, s[16:17]
	v_add_f32_e32 v33, v35, v43
	v_max3_f32 v32, v36, v40, v41
	v_cndmask_b32_e64 v43, v187, v33, s[18:19]
	v_max3_f32 v88, v32, v42, v43
	v_add_u32_e32 v32, 0xd7c, v218
	ds_read2_b32 v[32:33], v32 offset1:1
	v_add_u32_e32 v34, 0xd84, v218
	v_add_u32_e32 v36, 0xd8c, v218
	v_add_u32_e32 v38, 0xd94, v218
	ds_read2_b32 v[34:35], v34 offset1:1
	ds_read2_b32 v[36:37], v36 offset1:1
	ds_read2_b32 v[38:39], v38 offset1:1
	s_waitcnt lgkmcnt(3)
	v_add_f32_e32 v28, v28, v32
	v_cndmask_b32_e32 v89, v187, v28, vcc
	v_add_f32_e32 v28, v29, v33
	v_cndmask_b32_e64 v90, v187, v28, s[6:7]
	s_waitcnt lgkmcnt(2)
	v_add_f32_e32 v29, v30, v34
	v_max3_f32 v28, v88, v89, v90
	v_cndmask_b32_e64 v88, v187, v29, s[8:9]
	v_add_f32_e32 v29, v31, v35
	s_waitcnt lgkmcnt(1)
	v_add_f32_e32 v24, v24, v36
	v_cndmask_b32_e64 v91, v187, v29, s[10:11]
	v_cndmask_b32_e64 v92, v187, v24, s[12:13]
	v_add_f32_e32 v24, v25, v37
	s_waitcnt lgkmcnt(0)
	v_add_f32_e32 v25, v26, v38
	v_max3_f32 v28, v28, v88, v91
	v_cndmask_b32_e64 v93, v187, v24, s[14:15]
	v_cndmask_b32_e64 v94, v187, v25, s[16:17]
	v_add_f32_e32 v25, v27, v39
	v_max3_f32 v24, v28, v92, v93
	v_cndmask_b32_e64 v95, v187, v25, s[18:19]
	v_max3_f32 v32, v24, v94, v95
	v_add_u32_e32 v24, 0xe7c, v218
	ds_read2_b32 v[24:25], v24 offset1:1
	v_add_u32_e32 v26, 0xe84, v218
	v_add_u32_e32 v28, 0xe8c, v218
	v_add_u32_e32 v30, 0xe94, v218
	ds_read2_b32 v[26:27], v26 offset1:1
	ds_read2_b32 v[28:29], v28 offset1:1
	ds_read2_b32 v[30:31], v30 offset1:1
	s_waitcnt lgkmcnt(3)
	v_add_f32_e32 v20, v20, v24
	v_cndmask_b32_e32 v191, v187, v20, vcc
	v_add_f32_e32 v20, v21, v25
	s_waitcnt lgkmcnt(2)
	v_add_f32_e32 v21, v22, v26
	v_cndmask_b32_e64 v192, v187, v20, s[6:7]
	v_cndmask_b32_e64 v193, v187, v21, s[8:9]
	v_add_f32_e32 v21, v23, v27
	s_waitcnt lgkmcnt(1)
	v_add_f32_e32 v16, v16, v28
	v_max3_f32 v20, v32, v191, v192
	v_cndmask_b32_e64 v194, v187, v21, s[10:11]
	v_cndmask_b32_e64 v195, v187, v16, s[12:13]
	v_add_f32_e32 v16, v17, v29
	s_waitcnt lgkmcnt(0)
	v_add_f32_e32 v17, v18, v30
	v_max3_f32 v20, v20, v193, v194
	v_cndmask_b32_e64 v196, v187, v16, s[14:15]
	v_cndmask_b32_e64 v197, v187, v17, s[16:17]
	v_add_f32_e32 v17, v19, v31
	v_max3_f32 v16, v20, v195, v196
	v_cndmask_b32_e64 v198, v187, v17, s[18:19]
	v_max3_f32 v16, v16, v197, v198
	ds_bpermute_b32 v17, v186, v16
	s_waitcnt lgkmcnt(0)
	v_max_f32_e32 v17, v17, v17
	v_max_f32_e32 v16, v16, v17
	ds_bpermute_b32 v17, v168, v16
	s_waitcnt lgkmcnt(0)
	v_max_f32_e32 v17, v17, v17
	v_max_f32_e32 v199, v16, v17
	v_sub_f32_e32 v32, v66, v199
	v_exp_f32_e32 v66, v32
	v_sub_f32_e32 v32, v67, v199
	v_exp_f32_e32 v67, v32
	v_sub_f32_e32 v32, v68, v199
	v_exp_f32_e32 v68, v32
	v_sub_f32_e32 v32, v69, v199
	v_exp_f32_e32 v69, v32
	v_sub_f32_e32 v32, v62, v199
	v_exp_f32_e32 v226, v32
	v_sub_f32_e32 v32, v63, v199
	v_exp_f32_e32 v227, v32
	v_sub_f32_e32 v32, v64, v199
	v_exp_f32_e32 v228, v32
	v_sub_f32_e32 v32, v65, v199
	v_sub_f32_e32 v24, v50, v199
	v_exp_f32_e32 v229, v32
	v_sub_f32_e32 v32, v70, v199
	v_exp_f32_e32 v210, v24
	v_sub_f32_e32 v24, v51, v199
	v_exp_f32_e32 v230, v32
	v_sub_f32_e32 v32, v71, v199
	v_exp_f32_e32 v211, v24
	v_sub_f32_e32 v24, v52, v199
	v_exp_f32_e32 v231, v32
	v_sub_f32_e32 v32, v72, v199
	v_exp_f32_e32 v212, v24
	v_sub_f32_e32 v24, v53, v199
	v_exp_f32_e32 v232, v32
	v_sub_f32_e32 v32, v73, v199
	v_sub_f32_e32 v16, v219, v199
	v_sub_f32_e32 v20, v74, v199
	v_exp_f32_e32 v213, v24
	v_sub_f32_e32 v24, v44, v199
	v_sub_f32_e32 v28, v54, v199
	v_exp_f32_e32 v233, v32
	v_sub_f32_e32 v32, v40, v199
	v_sub_f32_e32 v40, v89, v199
	v_sub_f32_e32 v44, v191, v199
	v_exp_f32_e32 v200, v16
	v_sub_f32_e32 v16, v220, v199
	v_exp_f32_e32 v74, v20
	v_sub_f32_e32 v20, v75, v199
	v_exp_f32_e32 v218, v28
	v_sub_f32_e32 v28, v55, v199
	v_exp_f32_e32 v238, v40
	v_sub_f32_e32 v40, v90, v199
	v_exp_f32_e32 v246, v44
	v_sub_f32_e32 v44, v192, v199
	v_exp_f32_e32 v201, v16
	v_sub_f32_e32 v16, v82, v199
	v_exp_f32_e32 v75, v20
	v_sub_f32_e32 v20, v76, v199
	v_exp_f32_e32 v219, v28
	v_sub_f32_e32 v28, v56, v199
	v_exp_f32_e32 v239, v40
	v_sub_f32_e32 v40, v88, v199
	v_exp_f32_e32 v247, v44
	v_sub_f32_e32 v44, v193, v199
	v_exp_f32_e32 v82, v16
	v_sub_f32_e32 v16, v83, v199
	v_exp_f32_e32 v76, v20
	v_sub_f32_e32 v20, v77, v199
	v_exp_f32_e32 v220, v28
	v_sub_f32_e32 v28, v57, v199
	v_exp_f32_e32 v240, v40
	v_sub_f32_e32 v40, v91, v199
	v_exp_f32_e32 v248, v44
	v_sub_f32_e32 v44, v194, v199
	v_exp_f32_e32 v83, v16
	v_sub_f32_e32 v16, v84, v199
	v_exp_f32_e32 v77, v20
	v_sub_f32_e32 v20, v78, v199
	v_exp_f32_e32 v221, v28
	v_sub_f32_e32 v28, v58, v199
	v_exp_f32_e32 v241, v40
	v_sub_f32_e32 v40, v92, v199
	v_exp_f32_e32 v249, v44
	v_sub_f32_e32 v44, v195, v199
	v_exp_f32_e32 v84, v16
	v_sub_f32_e32 v16, v85, v199
	v_exp_f32_e32 v78, v20
	v_sub_f32_e32 v20, v79, v199
	v_exp_f32_e32 v214, v24
	v_sub_f32_e32 v24, v45, v199
	v_exp_f32_e32 v222, v28
	v_sub_f32_e32 v28, v59, v199
	v_exp_f32_e32 v234, v32
	v_sub_f32_e32 v32, v41, v199
	v_exp_f32_e32 v242, v40
; __device__ __forceinline__ void p2_attention(Frame& F, const bf16_t* Qg, const bf16_t* Kg, const bf16_t* Vg, bf16_t* MIX) {
;     ...
;                     const int fk = ((q >> 1) & 1) | (((jb + (q >> 2)) & 3) << 1), x0 = g ^ fk;
;                     const LAS unsigned char* ka = lds + AT_A + (wbase * 40 + o + 8 * (q >> 2) + (q & 3)) * 128;
;                     const LAS unsigned char* k0p = ka + x0 * 16;
;                     const LAS unsigned char* k1p = ka + (x0 ^ 4) * 16;
; #pragma unroll
;                     for (int wl = 0; wl < 8; ++wl)
; #pragma unroll
;                         for (int blk = 0; blk < 2; ++blk) {
;                             const bf16x8 k0 = *(const LAS bf16x8*)(k0p + wl * 5120 + blk * 512), k1 = *(const LAS bf16x8*)(k1p + wl * 5120 + blk * 512);
;                             f32x4 a = (f32x4){0.f, 0.f, 0.f, 0.f};
;                             a = __builtin_amdgcn_mfma_f32_16x16x32_bf16(k0, qf[jb][0], a, 0, 0, 0);
;                             a = __builtin_amdgcn_mfma_f32_16x16x32_bf16(k1, qf[jb][1], a, 0, 0, 0);
;                             sc[wl][blk] = a;
;                         }
;                 }
;                 const LAS float* tab = (const LAS float*)(lds + AT_TAB) + (rs - r + 7) * 64 + 16 + (kcol0 - cq + 15) + 8 * g;
;                 const int voff = kcol0 + 8 * g - cs;
;                 float mx = -INFINITY;
; #pragma unroll
;                 for (int wl = 0; wl < 8; ++wl)
; #pragma unroll
;                     for (int blk = 0; blk < 2; ++blk)
; #pragma unroll
;                         for (int e = 0; e < 4; ++e) {
;                             const int ep = 4 * blk + e;
;                             float s_ = sc[wl][blk][e] + tab[wl * 64 + ep];
;                             s_ = ((unsigned)(voff + ep) < 16u) ? s_ : -INFINITY;
;                             sc[wl][blk][e] = s_; mx = fmaxf(mx, s_);
;                         }
;                 mx = fmaxf(mx, __shfl_xor(mx, 16)); mx = fmaxf(mx, __shfl_xor(mx, 32));
;                 float l = 0.f;
; #pragma unroll
;                 for (int wl = 0; wl < 8; ++wl) {
;                     float p[8];
; #pragma unroll
;                     for (int blk = 0; blk < 2; ++blk)
; #pragma unroll
;                         for (int e = 0; e < 4; ++e) { p[4 * blk + e] = __builtin_amdgcn_exp2f(sc[wl][blk][e] - mx); l += p[4 * blk + e]; }
	v_sub_f32_e32 v40, v93, v199
	v_exp_f32_e32 v250, v44
	v_sub_f32_e32 v44, v196, v199
	v_exp_f32_e32 v85, v16
	v_sub_f32_e32 v16, v86, v199
	v_exp_f32_e32 v79, v20
	v_sub_f32_e32 v20, v80, v199
	v_exp_f32_e32 v215, v24
	v_sub_f32_e32 v24, v46, v199
	v_exp_f32_e32 v223, v28
	v_sub_f32_e32 v28, v60, v199
	v_exp_f32_e32 v235, v32
	v_sub_f32_e32 v32, v42, v199
	v_exp_f32_e32 v243, v40
	v_sub_f32_e32 v40, v94, v199
	v_exp_f32_e32 v191, v44
	v_sub_f32_e32 v44, v197, v199
	v_exp_f32_e32 v86, v16
	v_sub_f32_e32 v16, v87, v199
	v_exp_f32_e32 v80, v20
	v_sub_f32_e32 v20, v81, v199
	v_exp_f32_e32 v216, v24
	v_sub_f32_e32 v24, v47, v199
	v_exp_f32_e32 v224, v28
	v_sub_f32_e32 v28, v61, v199
	v_exp_f32_e32 v236, v32
	v_sub_f32_e32 v32, v43, v199
	v_exp_f32_e32 v244, v40
	v_sub_f32_e32 v40, v95, v199
	v_exp_f32_e32 v192, v44
	v_sub_f32_e32 v44, v198, v199
	v_exp_f32_e32 v87, v16
	v_cvt_pk_bf16_f32 v16, v200, v201
	v_cvt_pk_bf16_f32 v17, v82, v83
	v_cvt_pk_bf16_f32 v18, v84, v85
	v_cvt_pk_bf16_f32 v19, v86, v87
	v_exp_f32_e32 v81, v20
	v_cvt_pk_bf16_f32 v20, v74, v75
	v_cvt_pk_bf16_f32 v21, v76, v77
	v_cvt_pk_bf16_f32 v22, v78, v79
	v_cvt_pk_bf16_f32 v23, v80, v81
	v_exp_f32_e32 v217, v24
	v_cvt_pk_bf16_f32 v24, v210, v211
	v_cvt_pk_bf16_f32 v25, v212, v213
	v_cvt_pk_bf16_f32 v26, v214, v215
	v_cvt_pk_bf16_f32 v27, v216, v217
	v_exp_f32_e32 v225, v28
	v_cvt_pk_bf16_f32 v28, v218, v219
	v_cvt_pk_bf16_f32 v29, v220, v221
	v_cvt_pk_bf16_f32 v30, v222, v223
	v_cvt_pk_bf16_f32 v31, v224, v225
	v_cvt_pk_bf16_f32 v36, v66, v67
	v_cvt_pk_bf16_f32 v37, v68, v69
	v_cvt_pk_bf16_f32 v38, v226, v227
	v_cvt_pk_bf16_f32 v39, v228, v229
	v_exp_f32_e32 v237, v32
	v_cvt_pk_bf16_f32 v32, v230, v231
	v_cvt_pk_bf16_f32 v33, v232, v233
	v_cvt_pk_bf16_f32 v34, v234, v235
	v_cvt_pk_bf16_f32 v35, v236, v237
	v_exp_f32_e32 v245, v40
	v_cvt_pk_bf16_f32 v40, v238, v239
	v_cvt_pk_bf16_f32 v41, v240, v241
	v_cvt_pk_bf16_f32 v42, v242, v243
	v_cvt_pk_bf16_f32 v43, v244, v245
	v_exp_f32_e32 v193, v44
	v_cvt_pk_bf16_f32 v44, v246, v247
	v_cvt_pk_bf16_f32 v45, v248, v249
	v_cvt_pk_bf16_f32 v46, v250, v191
	v_cvt_pk_bf16_f32 v47, v192, v193
	ds_read_b128 v[50:53], v251 offset:1024
	ds_read_b128 v[54:57], v251 offset:1536
	s_waitcnt lgkmcnt(1)
	v_mfma_f32_16x16x32_bf16 v[50:53], v[50:53], v[8:11], 0
	ds_read_b128 v[58:61], v49 offset:1024
	ds_read_b128 v[62:65], v49 offset:1536
	s_waitcnt lgkmcnt(1)
	v_mfma_f32_16x16x32_bf16 v[194:197], v[58:61], v[12:15], v[50:53]
	s_nop 3
	v_add_f32_e32 v50, 0, v200
	v_add_f32_e32 v58, v201, v50
	ds_read_b128 v[50:53], v251 offset:6144
	v_add_f32_e32 v58, v82, v58
	v_mfma_f32_16x16x32_bf16 v[54:57], v[54:57], v[8:11], 0
	v_add_f32_e32 v70, v83, v58
	ds_read_b128 v[58:61], v49 offset:6144
	s_waitcnt lgkmcnt(2)
	v_mfma_f32_16x16x32_bf16 v[198:201], v[62:65], v[12:15], v[54:57]
	s_nop 3
	v_add_f32_e32 v54, v84, v70
	v_add_f32_e32 v62, v85, v54
	ds_read_b128 v[54:57], v251 offset:6656
	s_waitcnt lgkmcnt(2)
	v_mfma_f32_16x16x32_bf16 v[50:53], v[50:53], v[8:11], 0
	v_add_f32_e32 v62, v86, v62
	v_add_f32_e32 v70, v87, v62
	ds_read_b128 v[62:65], v49 offset:6656
	s_waitcnt lgkmcnt(2)
	v_mfma_f32_16x16x32_bf16 v[202:205], v[58:61], v[12:15], v[50:53]
	s_waitcnt lgkmcnt(1)
	v_mfma_f32_16x16x32_bf16 v[54:57], v[54:57], v[8:11], 0
	s_nop 0
	v_add_f32_e32 v50, v74, v70
	v_add_f32_e32 v58, v75, v50
	ds_read_b128 v[50:53], v251 offset:11264
	v_add_f32_e32 v58, v76, v58
	v_add_f32_e32 v70, v77, v58
	ds_read_b128 v[58:61], v49 offset:11264
	s_waitcnt lgkmcnt(2)
	v_mfma_f32_16x16x32_bf16 v[206:209], v[62:65], v[12:15], v[54:57]
	s_nop 2
	v_add_f32_e32 v54, v78, v70
	v_add_f32_e32 v62, v79, v54
	ds_read_b128 v[54:57], v251 offset:11776
	s_waitcnt lgkmcnt(2)
	v_mfma_f32_16x16x32_bf16 v[50:53], v[50:53], v[8:11], 0
	v_add_f32_e32 v62, v80, v62
	v_add_f32_e32 v70, v81, v62
	ds_read_b128 v[62:65], v49 offset:11776
	s_waitcnt lgkmcnt(2)
	v_mfma_f32_16x16x32_bf16 v[88:91], v[58:61], v[12:15], v[50:53]
	s_waitcnt lgkmcnt(1)
	v_mfma_f32_16x16x32_bf16 v[54:57], v[54:57], v[8:11], 0
	s_nop 0
	v_add_f32_e32 v50, v210, v70
	v_add_f32_e32 v58, v211, v50
	ds_read_b128 v[50:53], v251 offset:16384
	v_add_f32_e32 v58, v212, v58
	v_add_f32_e32 v70, v213, v58
	ds_read_b128 v[58:61], v49 offset:16384
	s_waitcnt lgkmcnt(2)
	v_mfma_f32_16x16x32_bf16 v[92:95], v[62:65], v[12:15], v[54:57]
	ds_read_b128 v[210:213], v251 offset:32256
	s_nop 1
	v_add_f32_e32 v54, v214, v70
	v_add_f32_e32 v62, v215, v54
	ds_read_b128 v[54:57], v251 offset:16896
	s_waitcnt lgkmcnt(3)
	v_mfma_f32_16x16x32_bf16 v[50:53], v[50:53], v[8:11], 0
	v_add_f32_e32 v62, v216, v62
	v_add_f32_e32 v70, v217, v62
	ds_read_b128 v[62:65], v49 offset:16896
	s_waitcnt lgkmcnt(3)
	v_mfma_f32_16x16x32_bf16 v[80:83], v[58:61], v[12:15], v[50:53]
	ds_read_b128 v[214:217], v49 offset:32256
	s_nop 1
	v_add_f32_e32 v50, v218, v70
	v_add_f32_e32 v58, v219, v50
	ds_read_b128 v[50:53], v251 offset:21504
	v_add_f32_e32 v58, v220, v58
	s_waitcnt lgkmcnt(3)
	v_mfma_f32_16x16x32_bf16 v[54:57], v[54:57], v[8:11], 0
	v_add_f32_e32 v70, v221, v58
	ds_read_b128 v[58:61], v49 offset:21504
	ds_read_b128 v[218:221], v49 offset:37376
	s_waitcnt lgkmcnt(4)
	v_mfma_f32_16x16x32_bf16 v[84:87], v[62:65], v[12:15], v[54:57]
	s_nop 2
	v_add_f32_e32 v54, v222, v70
	v_add_f32_e32 v62, v223, v54
	ds_read_b128 v[54:57], v251 offset:22016
	s_waitcnt lgkmcnt(3)
	v_mfma_f32_16x16x32_bf16 v[50:53], v[50:53], v[8:11], 0
	v_add_f32_e32 v62, v224, v62
	v_add_f32_e32 v70, v225, v62
	ds_read_b128 v[62:65], v49 offset:22016
	s_waitcnt lgkmcnt(3)
	v_mfma_f32_16x16x32_bf16 v[72:75], v[58:61], v[12:15], v[50:53]
	s_waitcnt lgkmcnt(1)
; #define LAS __attribute__((address_space(3)))
; __device__ __forceinline__ void p2_attention(Frame& F, const bf16_t* Qg, const bf16_t* Kg, const bf16_t* Vg, bf16_t* MIX) {
;     ...
; #pragma unroll
;                     for (int wl = 0; wl < 8; ++wl)
; #pragma unroll
;                         for (int blk = 0; blk < 2; ++blk) {
;                             const bf16x8 k0 = *(const LAS bf16x8*)(k0p + wl * 5120 + blk * 512), k1 = *(const LAS bf16x8*)(k1p + wl * 5120 + blk * 512);
;                             f32x4 a = (f32x4){0.f, 0.f, 0.f, 0.f};
;                             a = __builtin_amdgcn_mfma_f32_16x16x32_bf16(k0, qf[jb][0], a, 0, 0, 0);
;                             a = __builtin_amdgcn_mfma_f32_16x16x32_bf16(k1, qf[jb][1], a, 0, 0, 0);
;                             sc[wl][blk] = a;
;                         }
;                 }
;                 const LAS float* tab = (const LAS float*)(lds + AT_TAB) + (rs - r + 7) * 64 + 16 + (kcol0 - cq + 15) + 8 * g;
;                 const int voff = kcol0 + 8 * g - cs;
;                 float mx = -INFINITY;
; #pragma unroll
;                 for (int wl = 0; wl < 8; ++wl)
; #pragma unroll
;                     for (int blk = 0; blk < 2; ++blk)
; #pragma unroll
;                         for (int e = 0; e < 4; ++e) {
;                             const int ep = 4 * blk + e;
;                             float s_ = sc[wl][blk][e] + tab[wl * 64 + ep];
;                             s_ = ((unsigned)(voff + ep) < 16u) ? s_ : -INFINITY;
;                             sc[wl][blk][e] = s_; mx = fmaxf(mx, s_);
;                         }
;                 mx = fmaxf(mx, __shfl_xor(mx, 16)); mx = fmaxf(mx, __shfl_xor(mx, 32));
	v_mfma_f32_16x16x32_bf16 v[54:57], v[54:57], v[8:11], 0
	s_nop 0
	v_add_f32_e32 v50, v66, v70
	v_add_f32_e32 v58, v67, v50
	ds_read_b128 v[50:53], v251 offset:26624
	v_add_f32_e32 v58, v68, v58
	v_add_f32_e32 v66, v69, v58
	ds_read_b128 v[58:61], v49 offset:26624
	ds_read_b128 v[68:71], v49 offset:27136
	s_waitcnt lgkmcnt(3)
	v_mfma_f32_16x16x32_bf16 v[76:79], v[62:65], v[12:15], v[54:57]
	s_nop 2
	v_add_f32_e32 v54, v226, v66
	v_add_f32_e32 v62, v227, v54
	ds_read_b128 v[54:57], v251 offset:27136
	s_waitcnt lgkmcnt(3)
	v_mfma_f32_16x16x32_bf16 v[50:53], v[50:53], v[8:11], 0
	v_add_f32_e32 v62, v228, v62
	v_add_f32_e32 v62, v229, v62
	s_waitcnt lgkmcnt(2)
	v_mfma_f32_16x16x32_bf16 v[64:67], v[58:61], v[12:15], v[50:53]
	s_waitcnt lgkmcnt(0)
	v_mfma_f32_16x16x32_bf16 v[54:57], v[54:57], v[8:11], 0
	s_nop 1
	v_add_f32_e32 v50, v230, v62
	v_add_f32_e32 v58, v231, v50
	ds_read_b128 v[50:53], v251 offset:31744
	v_add_f32_e32 v58, v232, v58
	v_add_f32_e32 v62, v233, v58
	ds_read_b128 v[58:61], v49 offset:31744
	v_mfma_f32_16x16x32_bf16 v[68:71], v[68:71], v[12:15], v[54:57]
	s_nop 2
	v_add_f32_e32 v54, v234, v62
	s_waitcnt lgkmcnt(1)
	v_mfma_f32_16x16x32_bf16 v[50:53], v[50:53], v[8:11], 0
	v_add_f32_e32 v54, v235, v54
	v_add_f32_e32 v54, v236, v54
	v_add_f32_e32 v54, v237, v54
	s_waitcnt lgkmcnt(0)
	v_mfma_f32_16x16x32_bf16 v[56:59], v[58:61], v[12:15], v[50:53]
	v_mfma_f32_16x16x32_bf16 v[60:63], v[210:213], v[8:11], 0
	s_nop 1
	v_add_f32_e32 v50, v238, v54
	v_add_f32_e32 v54, v239, v50
	ds_read_b128 v[50:53], v251 offset:36864
	ds_read_b128 v[210:213], v49 offset:36864
	v_mfma_f32_16x16x32_bf16 v[60:63], v[214:217], v[12:15], v[60:63]
	ds_read_b128 v[214:217], v251 offset:37376
	v_add_f32_e32 v54, v240, v54
	v_add_f32_e32 v54, v241, v54
	v_add_f32_e32 v54, v242, v54
	s_waitcnt lgkmcnt(2)
	v_mfma_f32_16x16x32_bf16 v[50:53], v[50:53], v[8:11], 0
	v_add_f32_e32 v54, v243, v54
	v_add_f32_e32 v54, v244, v54
	v_add_f32_e32 v222, v245, v54
	s_waitcnt lgkmcnt(1)
	v_mfma_f32_16x16x32_bf16 v[52:55], v[210:213], v[12:15], v[50:53]
	v_add_f32_e32 v49, v246, v222
	v_add_f32_e32 v49, v247, v49
	v_add_f32_e32 v49, v248, v49
	s_waitcnt lgkmcnt(0)
	v_mfma_f32_16x16x32_bf16 v[210:213], v[214:217], v[8:11], 0
	v_add_f32_e32 v49, v249, v49
	v_or_b32_e32 v214, 16, v48
	v_add_f32_e32 v222, v250, v49
	v_mfma_f32_16x16x32_bf16 v[48:51], v[218:221], v[12:15], v[210:213]
	s_nop 3
	v_sub_u32_e32 v211, s0, v214
	v_lshl_add_u32 v189, v211, 2, v189
	v_min_u32_e32 v210, 56, v214
	v_add_u32_e32 v211, 0x79c, v189
	v_sub_u32_e32 v190, v190, v210
	ds_read2_b32 v[210:211], v211 offset1:1
	v_add_u32_e32 v212, 0x7a4, v189
	v_add_u32_e32 v214, 0x7ac, v189
	v_add_u32_e32 v216, 0x7b4, v189
	v_add_u32_e32 v218, 8, v190
	ds_read2_b32 v[212:213], v212 offset1:1
	ds_read2_b32 v[214:215], v214 offset1:1
	ds_read2_b32 v[216:217], v216 offset1:1
	s_waitcnt lgkmcnt(3)
	v_add_f32_e32 v194, v194, v210
	v_cmp_gt_u32_e32 vcc, 16, v218
	s_nop 1
	v_cndmask_b32_e32 v210, v187, v194, vcc
	v_add_f32_e32 v194, v195, v211
	v_add_u32_e32 v195, 9, v190
	v_cmp_gt_u32_e64 s[6:7], 16, v195
	s_waitcnt lgkmcnt(2)
	v_add_f32_e32 v195, v196, v212
	v_add_u32_e32 v196, 10, v190
	v_cmp_gt_u32_e64 s[8:9], 16, v196
	v_add_u32_e32 v196, 11, v190
	v_cmp_gt_u32_e64 s[10:11], 16, v196
	v_cndmask_b32_e64 v212, v187, v195, s[8:9]
	v_add_f32_e32 v195, v197, v213
	v_add_u32_e32 v196, 12, v190
	v_cndmask_b32_e64 v213, v187, v195, s[10:11]
	s_waitcnt lgkmcnt(1)
	v_add_f32_e32 v195, v198, v214
	v_cmp_gt_u32_e64 s[12:13], 16, v196
	v_add_u32_e32 v196, 13, v190
	v_cndmask_b32_e64 v211, v187, v194, s[6:7]
	v_cndmask_b32_e64 v214, v187, v195, s[12:13]
	v_add_f32_e32 v195, v199, v215
	v_cmp_gt_u32_e64 s[14:15], 16, v196
	v_add_u32_e32 v196, 14, v190
	v_max3_f32 v194, v210, s88, v211
	v_cndmask_b32_e64 v215, v187, v195, s[14:15]
	s_waitcnt lgkmcnt(0)
	v_add_f32_e32 v195, v200, v216
	v_cmp_gt_u32_e64 s[16:17], 16, v196
	v_add_u32_e32 v190, 15, v190
	v_max3_f32 v194, v194, v212, v213
	v_cndmask_b32_e64 v216, v187, v195, s[16:17]
	v_add_f32_e32 v195, v201, v217
	v_cmp_gt_u32_e64 s[18:19], 16, v190
	v_max3_f32 v194, v194, v214, v215
	v_add_u32_e32 v196, 0x8a4, v189
	v_cndmask_b32_e64 v190, v187, v195, s[18:19]
	v_max3_f32 v217, v194, v216, v190
	v_add_u32_e32 v194, 0x89c, v189
	ds_read2_b32 v[194:195], v194 offset1:1
	v_add_u32_e32 v198, 0x8ac, v189
	v_add_u32_e32 v200, 0x8b4, v189
	ds_read2_b32 v[196:197], v196 offset1:1
	ds_read2_b32 v[198:199], v198 offset1:1
	ds_read2_b32 v[200:201], v200 offset1:1
	s_waitcnt lgkmcnt(3)
	v_add_f32_e32 v194, v202, v194
	v_cndmask_b32_e32 v202, v187, v194, vcc
	v_add_f32_e32 v194, v203, v195
	s_waitcnt lgkmcnt(2)
	v_add_f32_e32 v195, v204, v196
	v_cndmask_b32_e64 v204, v187, v195, s[8:9]
	v_add_f32_e32 v195, v205, v197
	v_cndmask_b32_e64 v205, v187, v195, s[10:11]
	s_waitcnt lgkmcnt(1)
	v_add_f32_e32 v195, v206, v198
	v_cndmask_b32_e64 v203, v187, v194, s[6:7]
	v_cndmask_b32_e64 v206, v187, v195, s[12:13]
	v_add_f32_e32 v195, v207, v199
	v_max3_f32 v194, v217, v202, v203
	v_cndmask_b32_e64 v207, v187, v195, s[14:15]
	s_waitcnt lgkmcnt(0)
	v_add_f32_e32 v195, v208, v200
	v_max3_f32 v194, v194, v204, v205
	v_cndmask_b32_e64 v208, v187, v195, s[16:17]
	v_add_f32_e32 v195, v209, v201
	v_max3_f32 v194, v194, v206, v207
	v_cndmask_b32_e64 v209, v187, v195, s[18:19]
	v_max3_f32 v217, v194, v208, v209
	v_add_u32_e32 v194, 0x99c, v189
	ds_read2_b32 v[194:195], v194 offset1:1
	v_add_u32_e32 v196, 0x9a4, v189
	v_add_u32_e32 v198, 0x9ac, v189
	v_add_u32_e32 v200, 0x9b4, v189
	ds_read2_b32 v[196:197], v196 offset1:1
	ds_read2_b32 v[198:199], v198 offset1:1
	ds_read2_b32 v[200:201], v200 offset1:1
	s_waitcnt lgkmcnt(3)
; #define LAS __attribute__((address_space(3)))
; __device__ __forceinline__ void p2_attention(Frame& F, const bf16_t* Qg, const bf16_t* Kg, const bf16_t* Vg, bf16_t* MIX) {
;     ...
;                 const LAS float* tab = (const LAS float*)(lds + AT_TAB) + (rs - r + 7) * 64 + 16 + (kcol0 - cq + 15) + 8 * g;
;                 const int voff = kcol0 + 8 * g - cs;
;                 float mx = -INFINITY;
; #pragma unroll
;                 for (int wl = 0; wl < 8; ++wl)
; #pragma unroll
;                     for (int blk = 0; blk < 2; ++blk)
; #pragma unroll
;                         for (int e = 0; e < 4; ++e) {
;                             const int ep = 4 * blk + e;
;                             float s_ = sc[wl][blk][e] + tab[wl * 64 + ep];
;                             s_ = ((unsigned)(voff + ep) < 16u) ? s_ : -INFINITY;
;                             sc[wl][blk][e] = s_; mx = fmaxf(mx, s_);
;                         }
;                 mx = fmaxf(mx, __shfl_xor(mx, 16)); mx = fmaxf(mx, __shfl_xor(mx, 32));
	v_add_f32_e32 v88, v88, v194
	v_cndmask_b32_e32 v194, v187, v88, vcc
	v_add_f32_e32 v88, v89, v195
	s_waitcnt lgkmcnt(2)
	v_add_f32_e32 v89, v90, v196
	v_cndmask_b32_e64 v196, v187, v89, s[8:9]
	v_add_f32_e32 v89, v91, v197
	v_cndmask_b32_e64 v197, v187, v89, s[10:11]
	s_waitcnt lgkmcnt(1)
	v_add_f32_e32 v89, v92, v198
	v_cndmask_b32_e64 v195, v187, v88, s[6:7]
	v_cndmask_b32_e64 v198, v187, v89, s[12:13]
	v_add_f32_e32 v89, v93, v199
	v_max3_f32 v88, v217, v194, v195
	v_cndmask_b32_e64 v199, v187, v89, s[14:15]
	s_waitcnt lgkmcnt(0)
	v_add_f32_e32 v89, v94, v200
	v_max3_f32 v88, v88, v196, v197
	v_cndmask_b32_e64 v200, v187, v89, s[16:17]
	v_add_f32_e32 v89, v95, v201
	v_max3_f32 v88, v88, v198, v199
	v_cndmask_b32_e64 v201, v187, v89, s[18:19]
	v_max3_f32 v217, v88, v200, v201
	v_add_u32_e32 v88, 0xa9c, v189
	ds_read2_b32 v[88:89], v88 offset1:1
	v_add_u32_e32 v90, 0xaa4, v189
	v_add_u32_e32 v92, 0xaac, v189
	v_add_u32_e32 v94, 0xab4, v189
	ds_read2_b32 v[90:91], v90 offset1:1
	ds_read2_b32 v[92:93], v92 offset1:1
	ds_read2_b32 v[94:95], v94 offset1:1
	s_waitcnt lgkmcnt(3)
	v_add_f32_e32 v80, v80, v88
	v_cndmask_b32_e32 v88, v187, v80, vcc
	v_add_f32_e32 v80, v81, v89
	s_waitcnt lgkmcnt(2)
	v_add_f32_e32 v81, v82, v90
	v_cndmask_b32_e64 v90, v187, v81, s[8:9]
	v_add_f32_e32 v81, v83, v91
	v_cndmask_b32_e64 v91, v187, v81, s[10:11]
	s_waitcnt lgkmcnt(1)
	v_add_f32_e32 v81, v84, v92
	v_cndmask_b32_e64 v89, v187, v80, s[6:7]
	v_cndmask_b32_e64 v92, v187, v81, s[12:13]
	v_add_f32_e32 v81, v85, v93
	v_max3_f32 v80, v217, v88, v89
	v_cndmask_b32_e64 v93, v187, v81, s[14:15]
	s_waitcnt lgkmcnt(0)
	v_add_f32_e32 v81, v86, v94
	v_max3_f32 v80, v80, v90, v91
	v_cndmask_b32_e64 v94, v187, v81, s[16:17]
	v_add_f32_e32 v81, v87, v95
	v_max3_f32 v80, v80, v92, v93
	v_cndmask_b32_e64 v95, v187, v81, s[18:19]
	v_max3_f32 v217, v80, v94, v95
	v_add_u32_e32 v80, 0xb9c, v189
	ds_read2_b32 v[80:81], v80 offset1:1
	v_add_u32_e32 v82, 0xba4, v189
	v_add_u32_e32 v84, 0xbac, v189
	v_add_u32_e32 v86, 0xbb4, v189
	ds_read2_b32 v[82:83], v82 offset1:1
	ds_read2_b32 v[84:85], v84 offset1:1
	ds_read2_b32 v[86:87], v86 offset1:1
	s_waitcnt lgkmcnt(3)
	v_add_f32_e32 v72, v72, v80
	v_cndmask_b32_e32 v80, v187, v72, vcc
	v_add_f32_e32 v72, v73, v81
	v_cndmask_b32_e64 v81, v187, v72, s[6:7]
	s_waitcnt lgkmcnt(2)
	v_add_f32_e32 v73, v74, v82
	v_max3_f32 v72, v217, v80, v81
	v_cndmask_b32_e64 v217, v187, v73, s[8:9]
	v_add_f32_e32 v73, v75, v83
	v_cndmask_b32_e64 v218, v187, v73, s[10:11]
	s_waitcnt lgkmcnt(1)
	v_add_f32_e32 v73, v76, v84
	v_cndmask_b32_e64 v84, v187, v73, s[12:13]
	v_add_f32_e32 v73, v77, v85
	v_cndmask_b32_e64 v85, v187, v73, s[14:15]
	s_waitcnt lgkmcnt(0)
	v_add_f32_e32 v73, v78, v86
	v_max3_f32 v72, v72, v217, v218
	v_cndmask_b32_e64 v86, v187, v73, s[16:17]
	v_add_f32_e32 v73, v79, v87
	v_max3_f32 v72, v72, v84, v85
	v_cndmask_b32_e64 v87, v187, v73, s[18:19]
	v_max3_f32 v82, v72, v86, v87
	v_add_u32_e32 v72, 0xc9c, v189
	ds_read2_b32 v[72:73], v72 offset1:1
	v_add_u32_e32 v74, 0xca4, v189
	v_add_u32_e32 v76, 0xcac, v189
	v_add_u32_e32 v78, 0xcb4, v189
	ds_read2_b32 v[74:75], v74 offset1:1
	ds_read2_b32 v[76:77], v76 offset1:1
	ds_read2_b32 v[78:79], v78 offset1:1
	s_waitcnt lgkmcnt(3)
	v_add_f32_e32 v64, v64, v72
	v_cndmask_b32_e32 v72, v187, v64, vcc
	v_add_f32_e32 v64, v65, v73
	s_waitcnt lgkmcnt(2)
	v_add_f32_e32 v65, v66, v74
	v_cndmask_b32_e64 v74, v187, v65, s[8:9]
	v_add_f32_e32 v65, v67, v75
	v_cndmask_b32_e64 v75, v187, v65, s[10:11]
	s_waitcnt lgkmcnt(1)
	v_add_f32_e32 v65, v68, v76
	v_cndmask_b32_e64 v73, v187, v64, s[6:7]
	v_cndmask_b32_e64 v76, v187, v65, s[12:13]
	v_add_f32_e32 v65, v69, v77
	v_max3_f32 v64, v82, v72, v73
	v_cndmask_b32_e64 v77, v187, v65, s[14:15]
	s_waitcnt lgkmcnt(0)
	v_add_f32_e32 v65, v70, v78
	v_max3_f32 v64, v64, v74, v75
	v_cndmask_b32_e64 v78, v187, v65, s[16:17]
	v_add_f32_e32 v65, v71, v79
	v_max3_f32 v64, v64, v76, v77
	v_cndmask_b32_e64 v79, v187, v65, s[18:19]
	v_max3_f32 v82, v64, v78, v79
	v_add_u32_e32 v64, 0xd9c, v189
	ds_read2_b32 v[64:65], v64 offset1:1
	v_add_u32_e32 v66, 0xda4, v189
	v_add_u32_e32 v68, 0xdac, v189
	v_add_u32_e32 v70, 0xdb4, v189
	ds_read2_b32 v[66:67], v66 offset1:1
	ds_read2_b32 v[68:69], v68 offset1:1
	ds_read2_b32 v[70:71], v70 offset1:1
	s_waitcnt lgkmcnt(3)
	v_add_f32_e32 v56, v56, v64
	v_cndmask_b32_e32 v219, v187, v56, vcc
	v_add_f32_e32 v56, v57, v65
	s_waitcnt lgkmcnt(2)
	v_add_f32_e32 v57, v58, v66
	v_cndmask_b32_e64 v221, v187, v57, s[8:9]
	v_add_f32_e32 v57, v59, v67
	v_cndmask_b32_e64 v223, v187, v57, s[10:11]
	s_waitcnt lgkmcnt(1)
	v_add_f32_e32 v57, v60, v68
	v_cndmask_b32_e64 v220, v187, v56, s[6:7]
	v_cndmask_b32_e64 v224, v187, v57, s[12:13]
	v_add_f32_e32 v57, v61, v69
	v_max3_f32 v56, v82, v219, v220
	v_cndmask_b32_e64 v225, v187, v57, s[14:15]
	s_waitcnt lgkmcnt(0)
	v_add_f32_e32 v57, v62, v70
	v_max3_f32 v56, v56, v221, v223
	v_cndmask_b32_e64 v226, v187, v57, s[16:17]
	v_add_f32_e32 v57, v63, v71
	v_max3_f32 v56, v56, v224, v225
	v_cndmask_b32_e64 v227, v187, v57, s[18:19]
	v_max3_f32 v64, v56, v226, v227
	v_add_u32_e32 v56, 0xe9c, v189
	ds_read2_b32 v[56:57], v56 offset1:1
	v_add_u32_e32 v58, 0xea4, v189
	v_add_u32_e32 v60, 0xeac, v189
	v_add_u32_e32 v62, 0xeb4, v189
	ds_read2_b32 v[58:59], v58 offset1:1
	ds_read2_b32 v[60:61], v60 offset1:1
	ds_read2_b32 v[62:63], v62 offset1:1
	s_waitcnt lgkmcnt(3)
	v_add_f32_e32 v52, v52, v56
	v_cndmask_b32_e32 v189, v187, v52, vcc
	v_add_f32_e32 v52, v53, v57
	s_waitcnt lgkmcnt(2)
	v_add_f32_e32 v53, v54, v58
	v_cndmask_b32_e64 v228, v187, v52, s[6:7]
	v_cndmask_b32_e64 v229, v187, v53, s[8:9]
	v_add_f32_e32 v53, v55, v59
	s_waitcnt lgkmcnt(1)
; __device__ __forceinline__ unsigned cvt_pk_bf16(float lo, float hi) { unsigned r; asm volatile("v_cvt_pk_bf16_f32 %0, %1, %2" : "=v"(r) : "v"(lo), "v"(hi)); return r; }
; __device__ __forceinline__ void p2_attention(Frame& F, const bf16_t* Qg, const bf16_t* Kg, const bf16_t* Vg, bf16_t* MIX) {
;     ...
;                 mx = fmaxf(mx, __shfl_xor(mx, 16)); mx = fmaxf(mx, __shfl_xor(mx, 32));
;                 float l = 0.f;
; #pragma unroll
;                 for (int wl = 0; wl < 8; ++wl) {
;                     float p[8];
; #pragma unroll
;                     for (int blk = 0; blk < 2; ++blk)
; #pragma unroll
;                         for (int e = 0; e < 4; ++e) { p[4 * blk + e] = __builtin_amdgcn_exp2f(sc[wl][blk][e] - mx); l += p[4 * blk + e]; }
;                     pw[jb][wl].x = cvt_pk_bf16(p[0], p[1]); pw[jb][wl].y = cvt_pk_bf16(p[2], p[3]); pw[jb][wl].z = cvt_pk_bf16(p[4], p[5]); pw[jb][wl].w = cvt_pk_bf16(p[6], p[7]);
;                 }
;                 l += __shfl_xor(l, 16); l += __shfl_xor(l, 32);
;                 il[jb] = __builtin_amdgcn_rcpf(l);
	v_add_f32_e32 v48, v48, v60
	v_max3_f32 v52, v64, v189, v228
	v_cndmask_b32_e64 v230, v187, v53, s[10:11]
	v_cndmask_b32_e64 v231, v187, v48, s[12:13]
	v_add_f32_e32 v48, v49, v61
	s_waitcnt lgkmcnt(0)
	v_add_f32_e32 v49, v50, v62
	v_max3_f32 v52, v52, v229, v230
	v_cndmask_b32_e64 v232, v187, v48, s[14:15]
	v_cndmask_b32_e64 v233, v187, v49, s[16:17]
	v_add_f32_e32 v49, v51, v63
	v_max3_f32 v48, v52, v231, v232
	v_cndmask_b32_e64 v234, v187, v49, s[18:19]
	v_max3_f32 v48, v48, v233, v234
	ds_bpermute_b32 v49, v186, v48
	v_add_f32_e32 v50, v191, v222
	v_add_f32_e32 v50, v192, v50
	v_add_f32_e32 v50, v193, v50
	ds_bpermute_b32 v51, v186, v50
	s_waitcnt lgkmcnt(1)
	v_max_f32_e32 v49, v49, v49
	v_max_f32_e32 v48, v48, v49
	ds_bpermute_b32 v49, v168, v48
	s_waitcnt lgkmcnt(1)
	v_add_f32_e32 v82, v50, v51
	ds_bpermute_b32 v83, v168, v82
	s_waitcnt lgkmcnt(1)
	v_max_f32_e32 v49, v49, v49
	v_max_f32_e32 v191, v48, v49
	v_sub_f32_e32 v48, v210, v191
	v_exp_f32_e32 v48, v48
	v_sub_f32_e32 v49, v211, v191
	v_exp_f32_e32 v49, v49
	v_sub_f32_e32 v50, v212, v191
	v_exp_f32_e32 v50, v50
	v_sub_f32_e32 v51, v213, v191
	v_exp_f32_e32 v51, v51
	v_sub_f32_e32 v53, v214, v191
	v_add_f32_e32 v52, 0, v48
	v_exp_f32_e32 v53, v53
	v_sub_f32_e32 v54, v215, v191
	v_add_f32_e32 v52, v49, v52
	v_exp_f32_e32 v54, v54
	v_sub_f32_e32 v55, v216, v191
	v_add_f32_e32 v52, v50, v52
	v_exp_f32_e32 v55, v55
	v_sub_f32_e32 v56, v190, v191
	v_add_f32_e32 v52, v51, v52
	v_exp_f32_e32 v56, v56
	v_add_f32_e32 v52, v53, v52
	v_cvt_pk_bf16_f32 v48, v48, v49
	v_cvt_pk_bf16_f32 v49, v50, v51
	v_cvt_pk_bf16_f32 v50, v53, v54
	v_sub_f32_e32 v53, v202, v191
	v_add_f32_e32 v52, v54, v52
	v_exp_f32_e32 v53, v53
	v_sub_f32_e32 v54, v203, v191
	v_add_f32_e32 v52, v55, v52
	v_cvt_pk_bf16_f32 v51, v55, v56
	v_exp_f32_e32 v54, v54
	v_sub_f32_e32 v55, v204, v191
	v_add_f32_e32 v52, v56, v52
	v_exp_f32_e32 v55, v55
	v_sub_f32_e32 v56, v205, v191
	v_exp_f32_e32 v56, v56
	v_sub_f32_e32 v57, v206, v191
	v_add_f32_e32 v52, v53, v52
	v_exp_f32_e32 v57, v57
	v_sub_f32_e32 v58, v207, v191
	v_add_f32_e32 v52, v54, v52
	v_exp_f32_e32 v58, v58
	v_sub_f32_e32 v59, v208, v191
	v_add_f32_e32 v52, v55, v52
	v_exp_f32_e32 v59, v59
	v_sub_f32_e32 v60, v209, v191
	v_add_f32_e32 v52, v56, v52
	v_exp_f32_e32 v60, v60
	v_add_f32_e32 v52, v57, v52
	v_add_f32_e32 v52, v58, v52
	v_add_f32_e32 v52, v59, v52
	v_add_f32_e32 v61, v60, v52
	v_cvt_pk_bf16_f32 v52, v53, v54
	v_cvt_pk_bf16_f32 v53, v55, v56
	v_sub_f32_e32 v56, v194, v191
	v_exp_f32_e32 v56, v56
	v_cvt_pk_bf16_f32 v54, v57, v58
	v_sub_f32_e32 v57, v195, v191
	v_exp_f32_e32 v57, v57
	v_sub_f32_e32 v58, v196, v191
	v_cvt_pk_bf16_f32 v55, v59, v60
	v_exp_f32_e32 v58, v58
	v_sub_f32_e32 v59, v197, v191
	v_exp_f32_e32 v59, v59
	v_add_f32_e32 v60, v56, v61
	v_sub_f32_e32 v61, v198, v191
	v_exp_f32_e32 v61, v61
	v_sub_f32_e32 v62, v199, v191
	v_add_f32_e32 v60, v57, v60
	v_exp_f32_e32 v62, v62
	v_sub_f32_e32 v63, v200, v191
	v_add_f32_e32 v60, v58, v60
	v_exp_f32_e32 v63, v63
	v_sub_f32_e32 v64, v201, v191
	v_add_f32_e32 v60, v59, v60
	v_exp_f32_e32 v64, v64
	v_add_f32_e32 v60, v61, v60
	v_cvt_pk_bf16_f32 v56, v56, v57
	v_cvt_pk_bf16_f32 v57, v58, v59
	v_cvt_pk_bf16_f32 v58, v61, v62
	v_sub_f32_e32 v61, v88, v191
	v_add_f32_e32 v60, v62, v60
	v_exp_f32_e32 v61, v61
	v_sub_f32_e32 v62, v89, v191
	v_add_f32_e32 v60, v63, v60
	v_cvt_pk_bf16_f32 v59, v63, v64
	v_exp_f32_e32 v62, v62
	v_sub_f32_e32 v63, v90, v191
	v_add_f32_e32 v60, v64, v60
	v_exp_f32_e32 v63, v63
	v_sub_f32_e32 v64, v91, v191
	v_exp_f32_e32 v64, v64
	v_sub_f32_e32 v65, v92, v191
	v_add_f32_e32 v60, v61, v60
	v_exp_f32_e32 v65, v65
	v_sub_f32_e32 v66, v93, v191
	v_add_f32_e32 v60, v62, v60
	v_exp_f32_e32 v66, v66
	v_sub_f32_e32 v67, v94, v191
	v_add_f32_e32 v60, v63, v60
	v_exp_f32_e32 v67, v67
	v_sub_f32_e32 v68, v95, v191
	v_add_f32_e32 v60, v64, v60
	v_exp_f32_e32 v68, v68
	v_add_f32_e32 v60, v65, v60
	v_add_f32_e32 v60, v66, v60
	v_add_f32_e32 v60, v67, v60
	v_add_f32_e32 v69, v68, v60
	v_cvt_pk_bf16_f32 v60, v61, v62
	v_cvt_pk_bf16_f32 v61, v63, v64
	v_sub_f32_e32 v64, v80, v191
	v_exp_f32_e32 v64, v64
; __device__ __forceinline__ unsigned cvt_pk_bf16(float lo, float hi) { unsigned r; asm volatile("v_cvt_pk_bf16_f32 %0, %1, %2" : "=v"(r) : "v"(lo), "v"(hi)); return r; }
; #define ATT_WAIT_BAR() do { asm volatile("s_waitcnt vmcnt(0) lgkmcnt(0)" ::: "memory"); __builtin_amdgcn_s_barrier(); asm volatile("" ::: "memory"); } while (0)
; __device__ __forceinline__ void p2_attention(Frame& F, const bf16_t* Qg, const bf16_t* Kg, const bf16_t* Vg, bf16_t* MIX) {
;     ...
;                 float l = 0.f;
; #pragma unroll
;                 for (int wl = 0; wl < 8; ++wl) {
;                     float p[8];
; #pragma unroll
;                     for (int blk = 0; blk < 2; ++blk)
; #pragma unroll
;                         for (int e = 0; e < 4; ++e) { p[4 * blk + e] = __builtin_amdgcn_exp2f(sc[wl][blk][e] - mx); l += p[4 * blk + e]; }
;                     pw[jb][wl].x = cvt_pk_bf16(p[0], p[1]); pw[jb][wl].y = cvt_pk_bf16(p[2], p[3]); pw[jb][wl].z = cvt_pk_bf16(p[4], p[5]); pw[jb][wl].w = cvt_pk_bf16(p[6], p[7]);
;                 }
;                 l += __shfl_xor(l, 16); l += __shfl_xor(l, 32);
;                 il[jb] = __builtin_amdgcn_rcpf(l);
;             }
;             ATT_WAIT_BAR();
;             AttnUnit un = u; bf16x8 nq[2][2];
; #pragma unroll
;             for (int jb = 0; jb < 2; ++jb) { nq[jb][0] = qf[jb][0]; nq[jb][1] = qf[jb][1]; }
;             if (ui < UW - 1) {
;                 un = attn_decode(uidx + ui + 1);
;                 attn_dma<0>(lds0 + AT_A, Kg, un, wid, lane);
; #pragma unroll
;                 for (int jb = 0; jb < 2; ++jb) { const bf16_t* qp = Qg + ((size_t)(un.b * NHEAD + un.h) * SEQ + (un.r0 + wid) * 64 + 32 * un.jh + 16 * jb + q) * HD + 8 * g; nq[jb][0] = __builtin_nontemporal_load((const bf16x8*)qp); nq[jb][1] = __builtin_nontemporal_load((const bf16x8*)(qp + 32)); }
	v_cvt_pk_bf16_f32 v62, v65, v66
	v_sub_f32_e32 v65, v81, v191
	v_exp_f32_e32 v65, v65
	v_sub_f32_e32 v66, v217, v191
	v_cvt_pk_bf16_f32 v63, v67, v68
	v_exp_f32_e32 v66, v66
	v_sub_f32_e32 v67, v218, v191
	v_exp_f32_e32 v67, v67
	v_add_f32_e32 v68, v64, v69
	v_sub_f32_e32 v69, v84, v191
	v_exp_f32_e32 v69, v69
	v_sub_f32_e32 v70, v85, v191
	v_add_f32_e32 v68, v65, v68
	v_exp_f32_e32 v70, v70
	v_sub_f32_e32 v71, v86, v191
	v_add_f32_e32 v68, v66, v68
	v_exp_f32_e32 v71, v71
	v_add_f32_e32 v68, v67, v68
	v_sub_f32_e32 v80, v87, v191
	v_exp_f32_e32 v80, v80
	v_add_f32_e32 v68, v69, v68
	v_cvt_pk_bf16_f32 v64, v64, v65
	v_cvt_pk_bf16_f32 v65, v66, v67
	v_cvt_pk_bf16_f32 v66, v69, v70
	v_sub_f32_e32 v69, v72, v191
	v_add_f32_e32 v68, v70, v68
	v_exp_f32_e32 v69, v69
	v_sub_f32_e32 v70, v73, v191
	v_add_f32_e32 v68, v71, v68
	v_cvt_pk_bf16_f32 v67, v71, v80
	v_exp_f32_e32 v70, v70
	v_sub_f32_e32 v71, v74, v191
	v_exp_f32_e32 v71, v71
	v_sub_f32_e32 v72, v75, v191
	v_add_f32_e32 v68, v80, v68
	v_exp_f32_e32 v72, v72
	v_sub_f32_e32 v73, v76, v191
	v_add_f32_e32 v68, v69, v68
	v_exp_f32_e32 v73, v73
	v_sub_f32_e32 v74, v77, v191
	v_add_f32_e32 v68, v70, v68
	v_exp_f32_e32 v74, v74
	v_sub_f32_e32 v75, v78, v191
	v_add_f32_e32 v68, v71, v68
	v_exp_f32_e32 v75, v75
	v_sub_f32_e32 v76, v79, v191
	v_add_f32_e32 v68, v72, v68
	v_exp_f32_e32 v76, v76
	v_add_f32_e32 v68, v73, v68
	v_add_f32_e32 v68, v74, v68
	v_add_f32_e32 v68, v75, v68
	v_add_f32_e32 v77, v76, v68
	v_cvt_pk_bf16_f32 v68, v69, v70
	v_cvt_pk_bf16_f32 v69, v71, v72
	v_sub_f32_e32 v72, v219, v191
	v_exp_f32_e32 v72, v72
	v_cvt_pk_bf16_f32 v70, v73, v74
	v_sub_f32_e32 v73, v220, v191
	v_exp_f32_e32 v73, v73
	v_sub_f32_e32 v74, v221, v191
	v_cvt_pk_bf16_f32 v71, v75, v76
	v_exp_f32_e32 v74, v74
	v_sub_f32_e32 v75, v223, v191
	v_exp_f32_e32 v75, v75
	v_add_f32_e32 v76, v72, v77
	v_sub_f32_e32 v77, v224, v191
	v_exp_f32_e32 v77, v77
	v_sub_f32_e32 v78, v225, v191
	v_add_f32_e32 v76, v73, v76
	v_exp_f32_e32 v78, v78
	v_sub_f32_e32 v79, v226, v191
	v_add_f32_e32 v76, v74, v76
	v_exp_f32_e32 v79, v79
	v_sub_f32_e32 v80, v227, v191
	v_add_f32_e32 v76, v75, v76
	v_exp_f32_e32 v80, v80
	v_add_f32_e32 v76, v77, v76
	v_cvt_pk_bf16_f32 v72, v72, v73
	v_cvt_pk_bf16_f32 v73, v74, v75
	v_cvt_pk_bf16_f32 v74, v77, v78
	v_sub_f32_e32 v77, v189, v191
	v_add_f32_e32 v76, v78, v76
	v_exp_f32_e32 v77, v77
	v_sub_f32_e32 v78, v228, v191
	v_add_f32_e32 v76, v79, v76
	v_cvt_pk_bf16_f32 v75, v79, v80
	v_exp_f32_e32 v78, v78
	v_sub_f32_e32 v79, v229, v191
	v_add_f32_e32 v76, v80, v76
	v_exp_f32_e32 v79, v79
	v_sub_f32_e32 v80, v230, v191
	v_exp_f32_e32 v80, v80
	v_sub_f32_e32 v81, v231, v191
	v_add_f32_e32 v76, v77, v76
	v_exp_f32_e32 v81, v81
	v_sub_f32_e32 v84, v232, v191
	v_add_f32_e32 v76, v78, v76
	v_exp_f32_e32 v84, v84
	v_sub_f32_e32 v85, v233, v191
	v_add_f32_e32 v76, v79, v76
	v_exp_f32_e32 v85, v85
	v_sub_f32_e32 v86, v234, v191
	v_add_f32_e32 v76, v80, v76
	v_exp_f32_e32 v86, v86
	v_add_f32_e32 v76, v81, v76
	v_add_f32_e32 v76, v84, v76
	v_add_f32_e32 v76, v85, v76
	v_add_f32_e32 v87, v86, v76
	ds_bpermute_b32 v88, v186, v87
	v_cvt_pk_bf16_f32 v76, v77, v78
	v_cvt_pk_bf16_f32 v77, v79, v80
	v_cvt_pk_bf16_f32 v78, v81, v84
	v_cvt_pk_bf16_f32 v79, v85, v86
	s_waitcnt lgkmcnt(0)
	v_add_f32_e32 v80, v87, v88
	ds_bpermute_b32 v81, v168, v80
	s_waitcnt vmcnt(0) lgkmcnt(0)
	s_barrier
	s_cbranch_scc1 .LBB0_316
	s_and_b32 s90, s94, 56
	s_add_i32 s0, s44, s93
	v_sub_u32_e64 v188, s90, 4 clamp
	s_or_b32 s6, s90, 7
	s_add_i32 s1, s0, 9
	s_min_u32 s6, s6, 60
	v_readfirstlane_b32 s8, v188
	s_ashr_i32 s0, s1, 7
	s_sub_i32 s6, s6, s8
	s_and_b32 s95, s1, 1
	s_lshl_b32 s101, s95, 4
	s_lshr_b32 s101, s100, s101
	s_bfe_u32 s1, s1, 0x30004
	s_add_i32 s91, s6, 4
	s_lshl_b32 s6, s0, 3
	s_or_b32 s6, s6, s1
	s_ashr_i32 s7, s6, 31
	s_lshl_b32 s8, s8, 6
	s_mul_i32 s9, s95, 24
	s_lshl_b64 s[6:7], s[6:7], 12
	s_or_b32 s8, s8, s9
	s_or_b32 s8, s6, s8
	s_mov_b32 s9, s7
	s_lshl_b64 s[8:9], s[8:9], 7
	s_add_u32 s8, s40, s8
	s_mul_i32 s10, s91, 5
	s_addc_u32 s9, s41, s9
	s_cmp_ge_i32 s85, s10
	s_cbranch_scc0 .LBB0_317
	s_cmp_ge_i32 s43, s10
	s_cbranch_scc0 .LBB0_318

; __device__ __forceinline__ void glds16(const void* gsrc, unsigned lds_dst) { unsigned keep;
;     asm volatile("s_mov_b32 %0, m0\n\ts_mov_b32 m0, %2\n\ts_nop 0\n\tglobal_load_lds_dwordx4 %1, off\n\ts_mov_b32 m0, %0" : "=&s"(keep) : "v"(gsrc), "s"(lds_dst) : "memory"); }
; template <int KIND> __device__ __forceinline__ void attn_dma(unsigned dst, const bf16_t* src, const AttnUnit& u, int wid, int lane) {
;     const int np = u.nrows * 5;
;     const char* base = (const char*)(src + ((size_t)(u.b * NHEAD + u.h) * SEQ + u.krow_lo * 64 + 24 * u.jh) * HD);
; #pragma unroll
;     for (int it = 0; it < 10; ++it) {
;         const int pi = it * 8 + wid;
;         if (pi < np) {
;             const int w = (pi * 205) >> 10, p = pi - 5 * w, c = 8 * p + (lane >> 3);
;             const int sw = (KIND == 0) ? (((c >> 1) & 1) | (((c >> 3) & 3) << 1)) : ((((c >> 1) & 1) << 1) | (((c >> 3) & 1) << 2));
;             const int ch = (lane & 7) ^ sw;
;             const char* gp = base + (w * 64 + c) * (HD * 2) + ch * 16;
;             glds16(gp, (unsigned)__builtin_amdgcn_readfirstlane(dst + pi * 1024));
.LBB0_307:
	v_lshl_add_u64 v[18:19], v[16:17], 0, v[100:101]
	v_lshl_add_u64 v[18:19], v[18:19], 0, v[142:143]
	s_mov_b32 s6, m0
	s_mov_b32 m0, s36
	s_nop 0
	s_bitcmp1_b32 s101, 0
	s_cbranch_scc1 .Latt_def_v0
	global_load_lds_dwordx4 v[18:19], off nt
	s_branch .Latt_done_v0
.Latt_def_v0:
	global_load_lds_dwordx4 v[18:19], off
.Latt_done_v0:
	s_mov_b32 m0, s6
	s_cmp_ge_i32 s43, s1
	s_cbranch_scc1 .LBB0_287
.LBB0_308:
	v_lshl_add_u64 v[18:19], v[16:17], 0, v[104:105]
	v_lshl_add_u64 v[18:19], v[18:19], 0, v[144:145]
	s_mov_b32 s6, m0
	s_mov_b32 m0, s37
	s_nop 0
	s_bitcmp1_b32 s101, 1
	s_cbranch_scc1 .Latt_def_v1
	global_load_lds_dwordx4 v[18:19], off nt
	s_branch .Latt_done_v1

; __device__ __forceinline__ void glds16(const void* gsrc, unsigned lds_dst) { unsigned keep;
;     asm volatile("s_mov_b32 %0, m0\n\ts_mov_b32 m0, %2\n\ts_nop 0\n\tglobal_load_lds_dwordx4 %1, off\n\ts_mov_b32 m0, %0" : "=&s"(keep) : "v"(gsrc), "s"(lds_dst) : "memory"); }
; template <int KIND> __device__ __forceinline__ void attn_dma(unsigned dst, const bf16_t* src, const AttnUnit& u, int wid, int lane) {
;     const int np = u.nrows * 5;
;     const char* base = (const char*)(src + ((size_t)(u.b * NHEAD + u.h) * SEQ + u.krow_lo * 64 + 24 * u.jh) * HD);
; #pragma unroll
;     for (int it = 0; it < 10; ++it) {
;         const int pi = it * 8 + wid;
;         if (pi < np) {
;             const int w = (pi * 205) >> 10, p = pi - 5 * w, c = 8 * p + (lane >> 3);
;             const int sw = (KIND == 0) ? (((c >> 1) & 1) | (((c >> 3) & 3) << 1)) : ((((c >> 1) & 1) << 1) | (((c >> 3) & 1) << 2));
;             const int ch = (lane & 7) ^ sw;
;             const char* gp = base + (w * 64 + c) * (HD * 2) + ch * 16;
;             glds16(gp, (unsigned)__builtin_amdgcn_readfirstlane(dst + pi * 1024));
.Latt_done_v1:
	s_mov_b32 m0, s6
	s_cmp_ge_i32 s48, s1
	s_cbranch_scc1 .LBB0_288
.LBB0_309:
	v_lshl_add_u64 v[18:19], v[16:17], 0, v[108:109]
	v_lshl_add_u64 v[18:19], v[18:19], 0, v[146:147]
	s_mov_b32 s6, m0
	s_mov_b32 m0, s74
	s_nop 0
	s_bitcmp1_b32 s101, 2
	s_cbranch_scc1 .Latt_def_v2
	global_load_lds_dwordx4 v[18:19], off nt
	s_branch .Latt_done_v2

; __device__ __forceinline__ void glds16(const void* gsrc, unsigned lds_dst) { unsigned keep;
;     asm volatile("s_mov_b32 %0, m0\n\ts_mov_b32 m0, %2\n\ts_nop 0\n\tglobal_load_lds_dwordx4 %1, off\n\ts_mov_b32 m0, %0" : "=&s"(keep) : "v"(gsrc), "s"(lds_dst) : "memory"); }
; template <int KIND> __device__ __forceinline__ void attn_dma(unsigned dst, const bf16_t* src, const AttnUnit& u, int wid, int lane) {
;     const int np = u.nrows * 5;
;     const char* base = (const char*)(src + ((size_t)(u.b * NHEAD + u.h) * SEQ + u.krow_lo * 64 + 24 * u.jh) * HD);
; #pragma unroll
;     for (int it = 0; it < 10; ++it) {
;         const int pi = it * 8 + wid;
;         if (pi < np) {
;             const int w = (pi * 205) >> 10, p = pi - 5 * w, c = 8 * p + (lane >> 3);
;             const int sw = (KIND == 0) ? (((c >> 1) & 1) | (((c >> 3) & 3) << 1)) : ((((c >> 1) & 1) << 1) | (((c >> 3) & 1) << 2));
;             const int ch = (lane & 7) ^ sw;
;             const char* gp = base + (w * 64 + c) * (HD * 2) + ch * 16;
;             glds16(gp, (unsigned)__builtin_amdgcn_readfirstlane(dst + pi * 1024));
.Latt_done_v2:
	s_mov_b32 m0, s6
	s_cmp_ge_i32 s50, s1
	s_cbranch_scc1 .LBB0_289
.LBB0_310:
	v_lshl_add_u64 v[18:19], v[16:17], 0, v[112:113]
	v_lshl_add_u64 v[18:19], v[18:19], 0, v[148:149]
	s_mov_b32 s6, m0
	s_mov_b32 m0, s75
	s_nop 0
	s_bitcmp1_b32 s101, 3
	s_cbranch_scc1 .Latt_def_v3
	global_load_lds_dwordx4 v[18:19], off nt
	s_branch .Latt_done_v3

; __device__ __forceinline__ void glds16(const void* gsrc, unsigned lds_dst) { unsigned keep;
;     asm volatile("s_mov_b32 %0, m0\n\ts_mov_b32 m0, %2\n\ts_nop 0\n\tglobal_load_lds_dwordx4 %1, off\n\ts_mov_b32 m0, %0" : "=&s"(keep) : "v"(gsrc), "s"(lds_dst) : "memory"); }
; template <int KIND> __device__ __forceinline__ void attn_dma(unsigned dst, const bf16_t* src, const AttnUnit& u, int wid, int lane) {
;     const int np = u.nrows * 5;
;     const char* base = (const char*)(src + ((size_t)(u.b * NHEAD + u.h) * SEQ + u.krow_lo * 64 + 24 * u.jh) * HD);
; #pragma unroll
;     for (int it = 0; it < 10; ++it) {
;         const int pi = it * 8 + wid;
;         if (pi < np) {
;             const int w = (pi * 205) >> 10, p = pi - 5 * w, c = 8 * p + (lane >> 3);
;             const int sw = (KIND == 0) ? (((c >> 1) & 1) | (((c >> 3) & 3) << 1)) : ((((c >> 1) & 1) << 1) | (((c >> 3) & 1) << 2));
;             const int ch = (lane & 7) ^ sw;
;             const char* gp = base + (w * 64 + c) * (HD * 2) + ch * 16;
;             glds16(gp, (unsigned)__builtin_amdgcn_readfirstlane(dst + pi * 1024));
.Latt_done_v3:
	s_mov_b32 m0, s6
	s_cmp_ge_i32 s54, s1
	s_cbranch_scc1 .LBB0_290
.LBB0_311:
	v_lshl_add_u64 v[18:19], v[16:17], 0, v[116:117]
	v_lshl_add_u64 v[18:19], v[18:19], 0, v[150:151]
	s_mov_b32 s6, m0
	s_mov_b32 m0, s76
	s_nop 0
	s_bitcmp1_b32 s101, 4
	s_cbranch_scc1 .Latt_def_v4
	global_load_lds_dwordx4 v[18:19], off nt
	s_branch .Latt_done_v4

; __device__ __forceinline__ void glds16(const void* gsrc, unsigned lds_dst) { unsigned keep;
;     asm volatile("s_mov_b32 %0, m0\n\ts_mov_b32 m0, %2\n\ts_nop 0\n\tglobal_load_lds_dwordx4 %1, off\n\ts_mov_b32 m0, %0" : "=&s"(keep) : "v"(gsrc), "s"(lds_dst) : "memory"); }
; template <int KIND> __device__ __forceinline__ void attn_dma(unsigned dst, const bf16_t* src, const AttnUnit& u, int wid, int lane) {
;     const int np = u.nrows * 5;
;     const char* base = (const char*)(src + ((size_t)(u.b * NHEAD + u.h) * SEQ + u.krow_lo * 64 + 24 * u.jh) * HD);
; #pragma unroll
;     for (int it = 0; it < 10; ++it) {
;         const int pi = it * 8 + wid;
;         if (pi < np) {
;             const int w = (pi * 205) >> 10, p = pi - 5 * w, c = 8 * p + (lane >> 3);
;             const int sw = (KIND == 0) ? (((c >> 1) & 1) | (((c >> 3) & 3) << 1)) : ((((c >> 1) & 1) << 1) | (((c >> 3) & 1) << 2));
;             const int ch = (lane & 7) ^ sw;
;             const char* gp = base + (w * 64 + c) * (HD * 2) + ch * 16;
;             glds16(gp, (unsigned)__builtin_amdgcn_readfirstlane(dst + pi * 1024));
.Latt_done_v4:
	s_mov_b32 m0, s6
	s_cmp_ge_i32 s64, s1
	s_cbranch_scc1 .LBB0_291
.LBB0_312:
	v_lshl_add_u64 v[18:19], v[16:17], 0, v[120:121]
	v_lshl_add_u64 v[18:19], v[18:19], 0, v[152:153]
	s_mov_b32 s6, m0
	s_mov_b32 m0, s77
	s_nop 0
	s_bitcmp1_b32 s101, 5
	s_cbranch_scc1 .Latt_def_v5
	global_load_lds_dwordx4 v[18:19], off nt
	s_branch .Latt_done_v5

; __device__ __forceinline__ void glds16(const void* gsrc, unsigned lds_dst) { unsigned keep;
;     asm volatile("s_mov_b32 %0, m0\n\ts_mov_b32 m0, %2\n\ts_nop 0\n\tglobal_load_lds_dwordx4 %1, off\n\ts_mov_b32 m0, %0" : "=&s"(keep) : "v"(gsrc), "s"(lds_dst) : "memory"); }
; template <int KIND> __device__ __forceinline__ void attn_dma(unsigned dst, const bf16_t* src, const AttnUnit& u, int wid, int lane) {
;     const int np = u.nrows * 5;
;     const char* base = (const char*)(src + ((size_t)(u.b * NHEAD + u.h) * SEQ + u.krow_lo * 64 + 24 * u.jh) * HD);
; #pragma unroll
;     for (int it = 0; it < 10; ++it) {
;         const int pi = it * 8 + wid;
;         if (pi < np) {
;             const int w = (pi * 205) >> 10, p = pi - 5 * w, c = 8 * p + (lane >> 3);
;             const int sw = (KIND == 0) ? (((c >> 1) & 1) | (((c >> 3) & 3) << 1)) : ((((c >> 1) & 1) << 1) | (((c >> 3) & 1) << 2));
;             const int ch = (lane & 7) ^ sw;
;             const char* gp = base + (w * 64 + c) * (HD * 2) + ch * 16;
;             glds16(gp, (unsigned)__builtin_amdgcn_readfirstlane(dst + pi * 1024));
.Latt_done_v5:
	s_mov_b32 m0, s6
	s_cmp_ge_i32 s66, s1
	s_cbranch_scc1 .LBB0_292
.LBB0_313:
	v_lshl_add_u64 v[18:19], v[16:17], 0, v[124:125]
	v_lshl_add_u64 v[18:19], v[18:19], 0, v[154:155]
	s_mov_b32 s6, m0
	s_mov_b32 m0, s78
	s_nop 0
	s_bitcmp1_b32 s101, 6
	s_cbranch_scc1 .Latt_def_v6
	global_load_lds_dwordx4 v[18:19], off nt
	s_branch .Latt_done_v6

; __device__ __forceinline__ void glds16(const void* gsrc, unsigned lds_dst) { unsigned keep;
;     asm volatile("s_mov_b32 %0, m0\n\ts_mov_b32 m0, %2\n\ts_nop 0\n\tglobal_load_lds_dwordx4 %1, off\n\ts_mov_b32 m0, %0" : "=&s"(keep) : "v"(gsrc), "s"(lds_dst) : "memory"); }
; template <int KIND> __device__ __forceinline__ void attn_dma(unsigned dst, const bf16_t* src, const AttnUnit& u, int wid, int lane) {
;     const int np = u.nrows * 5;
;     const char* base = (const char*)(src + ((size_t)(u.b * NHEAD + u.h) * SEQ + u.krow_lo * 64 + 24 * u.jh) * HD);
; #pragma unroll
;     for (int it = 0; it < 10; ++it) {
;         const int pi = it * 8 + wid;
;         if (pi < np) {
;             const int w = (pi * 205) >> 10, p = pi - 5 * w, c = 8 * p + (lane >> 3);
;             const int sw = (KIND == 0) ? (((c >> 1) & 1) | (((c >> 3) & 3) << 1)) : ((((c >> 1) & 1) << 1) | (((c >> 3) & 1) << 2));
;             const int ch = (lane & 7) ^ sw;
;             const char* gp = base + (w * 64 + c) * (HD * 2) + ch * 16;
;             glds16(gp, (unsigned)__builtin_amdgcn_readfirstlane(dst + pi * 1024));
.Latt_done_v6:
	s_mov_b32 m0, s6
	s_cmp_ge_i32 s68, s1
	s_cbranch_scc1 .LBB0_293
.LBB0_314:
	v_lshl_add_u64 v[18:19], v[16:17], 0, v[128:129]
	v_lshl_add_u64 v[18:19], v[18:19], 0, v[156:157]
	s_mov_b32 s6, m0
	s_mov_b32 m0, s79
	s_nop 0
	s_bitcmp1_b32 s101, 7
	s_cbranch_scc1 .Latt_def_v7
	global_load_lds_dwordx4 v[18:19], off nt
	s_branch .Latt_done_v7

; __device__ __forceinline__ void glds16(const void* gsrc, unsigned lds_dst) { unsigned keep;
;     asm volatile("s_mov_b32 %0, m0\n\ts_mov_b32 m0, %2\n\ts_nop 0\n\tglobal_load_lds_dwordx4 %1, off\n\ts_mov_b32 m0, %0" : "=&s"(keep) : "v"(gsrc), "s"(lds_dst) : "memory"); }
; template <int KIND> __device__ __forceinline__ void attn_dma(unsigned dst, const bf16_t* src, const AttnUnit& u, int wid, int lane) {
;     const int np = u.nrows * 5;
;     const char* base = (const char*)(src + ((size_t)(u.b * NHEAD + u.h) * SEQ + u.krow_lo * 64 + 24 * u.jh) * HD);
; #pragma unroll
;     for (int it = 0; it < 10; ++it) {
;         const int pi = it * 8 + wid;
;         if (pi < np) {
;             const int w = (pi * 205) >> 10, p = pi - 5 * w, c = 8 * p + (lane >> 3);
;             const int sw = (KIND == 0) ? (((c >> 1) & 1) | (((c >> 3) & 3) << 1)) : ((((c >> 1) & 1) << 1) | (((c >> 3) & 1) << 2));
;             const int ch = (lane & 7) ^ sw;
;             const char* gp = base + (w * 64 + c) * (HD * 2) + ch * 16;
;             glds16(gp, (unsigned)__builtin_amdgcn_readfirstlane(dst + pi * 1024));
.Latt_done_v7:
	s_mov_b32 m0, s6
	s_cmp_ge_i32 s70, s1
	s_cbranch_scc1 .LBB0_294
.LBB0_315:
	v_lshl_add_u64 v[18:19], v[16:17], 0, v[132:133]
	v_lshl_add_u64 v[18:19], v[18:19], 0, v[158:159]
	s_mov_b32 s6, m0
	s_mov_b32 m0, s80
	s_nop 0
	s_bitcmp1_b32 s101, 8
	s_cbranch_scc1 .Latt_def_v8
	global_load_lds_dwordx4 v[18:19], off nt
	s_branch .Latt_done_v8

; __device__ __forceinline__ void glds16(const void* gsrc, unsigned lds_dst) { unsigned keep;
;     asm volatile("s_mov_b32 %0, m0\n\ts_mov_b32 m0, %2\n\ts_nop 0\n\tglobal_load_lds_dwordx4 %1, off\n\ts_mov_b32 m0, %0" : "=&s"(keep) : "v"(gsrc), "s"(lds_dst) : "memory"); }
; template <int KIND> __device__ __forceinline__ void attn_dma(unsigned dst, const bf16_t* src, const AttnUnit& u, int wid, int lane) {
;     const int np = u.nrows * 5;
;     const char* base = (const char*)(src + ((size_t)(u.b * NHEAD + u.h) * SEQ + u.krow_lo * 64 + 24 * u.jh) * HD);
; #pragma unroll
;     for (int it = 0; it < 10; ++it) {
;         const int pi = it * 8 + wid;
;         if (pi < np) {
;             const int w = (pi * 205) >> 10, p = pi - 5 * w, c = 8 * p + (lane >> 3);
;             const int sw = (KIND == 0) ? (((c >> 1) & 1) | (((c >> 3) & 3) << 1)) : ((((c >> 1) & 1) << 1) | (((c >> 3) & 1) << 2));
;             const int ch = (lane & 7) ^ sw;
;             const char* gp = base + (w * 64 + c) * (HD * 2) + ch * 16;
;             glds16(gp, (unsigned)__builtin_amdgcn_readfirstlane(dst + pi * 1024));
.Latt_done_v8:
	s_mov_b32 m0, s6
	s_cmp_ge_i32 s72, s1
	s_cbranch_scc0 .LBB0_295
	s_branch .LBB0_296

; __device__ __forceinline__ void glds16(const void* gsrc, unsigned lds_dst) { unsigned keep;
;     asm volatile("s_mov_b32 %0, m0\n\ts_mov_b32 m0, %2\n\ts_nop 0\n\tglobal_load_lds_dwordx4 %1, off\n\ts_mov_b32 m0, %0" : "=&s"(keep) : "v"(gsrc), "s"(lds_dst) : "memory"); }
; template <int KIND> __device__ __forceinline__ void attn_dma(unsigned dst, const bf16_t* src, const AttnUnit& u, int wid, int lane) {
;     const int np = u.nrows * 5;
;     const char* base = (const char*)(src + ((size_t)(u.b * NHEAD + u.h) * SEQ + u.krow_lo * 64 + 24 * u.jh) * HD);
; #pragma unroll
;     for (int it = 0; it < 10; ++it) {
;         const int pi = it * 8 + wid;
;         if (pi < np) {
;             const int w = (pi * 205) >> 10, p = pi - 5 * w, c = 8 * p + (lane >> 3);
;             const int sw = (KIND == 0) ? (((c >> 1) & 1) | (((c >> 3) & 3) << 1)) : ((((c >> 1) & 1) << 1) | (((c >> 3) & 1) << 2));
;             const int ch = (lane & 7) ^ sw;
;             const char* gp = base + (w * 64 + c) * (HD * 2) + ch * 16;
;             glds16(gp, (unsigned)__builtin_amdgcn_readfirstlane(dst + pi * 1024));
; __device__ __forceinline__ void p2_attention(Frame& F, const bf16_t* Qg, const bf16_t* Kg, const bf16_t* Vg, bf16_t* MIX) {
;     ...
;                 attn_dma<0>(lds0 + AT_A, Kg, un, wid, lane);
.LBB0_317:
	v_lshl_add_u64 v[0:1], s[8:9], 0, v[100:101]
	v_lshl_add_u64 v[0:1], v[0:1], 0, v[102:103]
	s_mov_b32 s11, m0
	s_mov_b32 m0, s42
	s_nop 0
	s_bitcmp1_b32 s101, 0
	s_cbranch_scc1 .Latt_def_nk0
	global_load_lds_dwordx4 v[0:1], off nt
	s_branch .Latt_done_nk0

; __device__ __forceinline__ void glds16(const void* gsrc, unsigned lds_dst) { unsigned keep;
;     asm volatile("s_mov_b32 %0, m0\n\ts_mov_b32 m0, %2\n\ts_nop 0\n\tglobal_load_lds_dwordx4 %1, off\n\ts_mov_b32 m0, %0" : "=&s"(keep) : "v"(gsrc), "s"(lds_dst) : "memory"); }
; template <int KIND> __device__ __forceinline__ void attn_dma(unsigned dst, const bf16_t* src, const AttnUnit& u, int wid, int lane) {
;     const int np = u.nrows * 5;
;     const char* base = (const char*)(src + ((size_t)(u.b * NHEAD + u.h) * SEQ + u.krow_lo * 64 + 24 * u.jh) * HD);
; #pragma unroll
;     for (int it = 0; it < 10; ++it) {
;         const int pi = it * 8 + wid;
;         if (pi < np) {
;             const int w = (pi * 205) >> 10, p = pi - 5 * w, c = 8 * p + (lane >> 3);
;             const int sw = (KIND == 0) ? (((c >> 1) & 1) | (((c >> 3) & 3) << 1)) : ((((c >> 1) & 1) << 1) | (((c >> 3) & 1) << 2));
;             const int ch = (lane & 7) ^ sw;
;             const char* gp = base + (w * 64 + c) * (HD * 2) + ch * 16;
;             glds16(gp, (unsigned)__builtin_amdgcn_readfirstlane(dst + pi * 1024));
; __device__ __forceinline__ void p2_attention(Frame& F, const bf16_t* Qg, const bf16_t* Kg, const bf16_t* Vg, bf16_t* MIX) {
;     ...
;                 attn_dma<0>(lds0 + AT_A, Kg, un, wid, lane);
.Latt_done_nk0:
	s_mov_b32 m0, s11
	s_cmp_ge_i32 s43, s10
	s_cbranch_scc1 .LBB0_299
.LBB0_318:
	v_lshl_add_u64 v[0:1], s[8:9], 0, v[104:105]
	v_lshl_add_u64 v[0:1], v[0:1], 0, v[106:107]
	s_mov_b32 s11, m0
	s_mov_b32 m0, s45
	s_nop 0
	s_bitcmp1_b32 s101, 1
	s_cbranch_scc1 .Latt_def_nk1
	global_load_lds_dwordx4 v[0:1], off nt
	s_branch .Latt_done_nk1

; __device__ __forceinline__ void glds16(const void* gsrc, unsigned lds_dst) { unsigned keep;
;     asm volatile("s_mov_b32 %0, m0\n\ts_mov_b32 m0, %2\n\ts_nop 0\n\tglobal_load_lds_dwordx4 %1, off\n\ts_mov_b32 m0, %0" : "=&s"(keep) : "v"(gsrc), "s"(lds_dst) : "memory"); }
; template <int KIND> __device__ __forceinline__ void attn_dma(unsigned dst, const bf16_t* src, const AttnUnit& u, int wid, int lane) {
;     const int np = u.nrows * 5;
;     const char* base = (const char*)(src + ((size_t)(u.b * NHEAD + u.h) * SEQ + u.krow_lo * 64 + 24 * u.jh) * HD);
; #pragma unroll
;     for (int it = 0; it < 10; ++it) {
;         const int pi = it * 8 + wid;
;         if (pi < np) {
;             const int w = (pi * 205) >> 10, p = pi - 5 * w, c = 8 * p + (lane >> 3);
;             const int sw = (KIND == 0) ? (((c >> 1) & 1) | (((c >> 3) & 3) << 1)) : ((((c >> 1) & 1) << 1) | (((c >> 3) & 1) << 2));
;             const int ch = (lane & 7) ^ sw;
;             const char* gp = base + (w * 64 + c) * (HD * 2) + ch * 16;
;             glds16(gp, (unsigned)__builtin_amdgcn_readfirstlane(dst + pi * 1024));
; __device__ __forceinline__ void p2_attention(Frame& F, const bf16_t* Qg, const bf16_t* Kg, const bf16_t* Vg, bf16_t* MIX) {
;     ...
;                 attn_dma<0>(lds0 + AT_A, Kg, un, wid, lane);
.Latt_done_nk1:
	s_mov_b32 m0, s11
	s_cmp_ge_i32 s48, s10
	s_cbranch_scc1 .LBB0_300
.LBB0_319:
	v_lshl_add_u64 v[0:1], s[8:9], 0, v[108:109]
	v_lshl_add_u64 v[0:1], v[0:1], 0, v[110:111]
	s_mov_b32 s11, m0
	s_mov_b32 m0, s49
	s_nop 0
	s_bitcmp1_b32 s101, 2
	s_cbranch_scc1 .Latt_def_nk2
	global_load_lds_dwordx4 v[0:1], off nt
	s_branch .Latt_done_nk2

; __device__ __forceinline__ void glds16(const void* gsrc, unsigned lds_dst) { unsigned keep;
;     asm volatile("s_mov_b32 %0, m0\n\ts_mov_b32 m0, %2\n\ts_nop 0\n\tglobal_load_lds_dwordx4 %1, off\n\ts_mov_b32 m0, %0" : "=&s"(keep) : "v"(gsrc), "s"(lds_dst) : "memory"); }
; template <int KIND> __device__ __forceinline__ void attn_dma(unsigned dst, const bf16_t* src, const AttnUnit& u, int wid, int lane) {
;     const int np = u.nrows * 5;
;     const char* base = (const char*)(src + ((size_t)(u.b * NHEAD + u.h) * SEQ + u.krow_lo * 64 + 24 * u.jh) * HD);
; #pragma unroll
;     for (int it = 0; it < 10; ++it) {
;         const int pi = it * 8 + wid;
;         if (pi < np) {
;             const int w = (pi * 205) >> 10, p = pi - 5 * w, c = 8 * p + (lane >> 3);
;             const int sw = (KIND == 0) ? (((c >> 1) & 1) | (((c >> 3) & 3) << 1)) : ((((c >> 1) & 1) << 1) | (((c >> 3) & 1) << 2));
;             const int ch = (lane & 7) ^ sw;
;             const char* gp = base + (w * 64 + c) * (HD * 2) + ch * 16;
;             glds16(gp, (unsigned)__builtin_amdgcn_readfirstlane(dst + pi * 1024));
; __device__ __forceinline__ void p2_attention(Frame& F, const bf16_t* Qg, const bf16_t* Kg, const bf16_t* Vg, bf16_t* MIX) {
;     ...
;                 attn_dma<0>(lds0 + AT_A, Kg, un, wid, lane);
.Latt_done_nk2:
	s_mov_b32 m0, s11
	s_cmp_ge_i32 s50, s10
	s_cbranch_scc1 .LBB0_301
.LBB0_320:
	v_lshl_add_u64 v[0:1], s[8:9], 0, v[112:113]
	v_lshl_add_u64 v[0:1], v[0:1], 0, v[114:115]
	s_mov_b32 s11, m0
	s_mov_b32 m0, s51
	s_nop 0
	s_bitcmp1_b32 s101, 3
	s_cbranch_scc1 .Latt_def_nk3
	global_load_lds_dwordx4 v[0:1], off nt
	s_branch .Latt_done_nk3

; __device__ __forceinline__ void glds16(const void* gsrc, unsigned lds_dst) { unsigned keep;
;     asm volatile("s_mov_b32 %0, m0\n\ts_mov_b32 m0, %2\n\ts_nop 0\n\tglobal_load_lds_dwordx4 %1, off\n\ts_mov_b32 m0, %0" : "=&s"(keep) : "v"(gsrc), "s"(lds_dst) : "memory"); }
; template <int KIND> __device__ __forceinline__ void attn_dma(unsigned dst, const bf16_t* src, const AttnUnit& u, int wid, int lane) {
;     const int np = u.nrows * 5;
;     const char* base = (const char*)(src + ((size_t)(u.b * NHEAD + u.h) * SEQ + u.krow_lo * 64 + 24 * u.jh) * HD);
; #pragma unroll
;     for (int it = 0; it < 10; ++it) {
;         const int pi = it * 8 + wid;
;         if (pi < np) {
;             const int w = (pi * 205) >> 10, p = pi - 5 * w, c = 8 * p + (lane >> 3);
;             const int sw = (KIND == 0) ? (((c >> 1) & 1) | (((c >> 3) & 3) << 1)) : ((((c >> 1) & 1) << 1) | (((c >> 3) & 1) << 2));
;             const int ch = (lane & 7) ^ sw;
;             const char* gp = base + (w * 64 + c) * (HD * 2) + ch * 16;
;             glds16(gp, (unsigned)__builtin_amdgcn_readfirstlane(dst + pi * 1024));
; __device__ __forceinline__ void p2_attention(Frame& F, const bf16_t* Qg, const bf16_t* Kg, const bf16_t* Vg, bf16_t* MIX) {
;     ...
;                 attn_dma<0>(lds0 + AT_A, Kg, un, wid, lane);
.Latt_done_nk3:
	s_mov_b32 m0, s11
	s_cmp_ge_i32 s54, s10
	s_cbranch_scc1 .LBB0_302
.LBB0_321:
	v_lshl_add_u64 v[0:1], s[8:9], 0, v[116:117]
	v_lshl_add_u64 v[0:1], v[0:1], 0, v[118:119]
	s_mov_b32 s11, m0
	s_mov_b32 m0, s55
	s_nop 0
	s_bitcmp1_b32 s101, 4
	s_cbranch_scc1 .Latt_def_nk4
	global_load_lds_dwordx4 v[0:1], off nt
	s_branch .Latt_done_nk4

; __device__ __forceinline__ void glds16(const void* gsrc, unsigned lds_dst) { unsigned keep;
;     asm volatile("s_mov_b32 %0, m0\n\ts_mov_b32 m0, %2\n\ts_nop 0\n\tglobal_load_lds_dwordx4 %1, off\n\ts_mov_b32 m0, %0" : "=&s"(keep) : "v"(gsrc), "s"(lds_dst) : "memory"); }
; template <int KIND> __device__ __forceinline__ void attn_dma(unsigned dst, const bf16_t* src, const AttnUnit& u, int wid, int lane) {
;     const int np = u.nrows * 5;
;     const char* base = (const char*)(src + ((size_t)(u.b * NHEAD + u.h) * SEQ + u.krow_lo * 64 + 24 * u.jh) * HD);
; #pragma unroll
;     for (int it = 0; it < 10; ++it) {
;         const int pi = it * 8 + wid;
;         if (pi < np) {
;             const int w = (pi * 205) >> 10, p = pi - 5 * w, c = 8 * p + (lane >> 3);
;             const int sw = (KIND == 0) ? (((c >> 1) & 1) | (((c >> 3) & 3) << 1)) : ((((c >> 1) & 1) << 1) | (((c >> 3) & 1) << 2));
;             const int ch = (lane & 7) ^ sw;
;             const char* gp = base + (w * 64 + c) * (HD * 2) + ch * 16;
;             glds16(gp, (unsigned)__builtin_amdgcn_readfirstlane(dst + pi * 1024));
; __device__ __forceinline__ void p2_attention(Frame& F, const bf16_t* Qg, const bf16_t* Kg, const bf16_t* Vg, bf16_t* MIX) {
;     ...
;                 attn_dma<0>(lds0 + AT_A, Kg, un, wid, lane);
.Latt_done_nk4:
	s_mov_b32 m0, s11
	s_cmp_ge_i32 s64, s10
	s_cbranch_scc1 .LBB0_303
.LBB0_322:
	v_lshl_add_u64 v[0:1], s[8:9], 0, v[120:121]
	v_lshl_add_u64 v[0:1], v[0:1], 0, v[122:123]
	s_mov_b32 s11, m0
	s_mov_b32 m0, s65
	s_nop 0
	s_bitcmp1_b32 s101, 5
	s_cbranch_scc1 .Latt_def_nk5
	global_load_lds_dwordx4 v[0:1], off nt
	s_branch .Latt_done_nk5

; __device__ __forceinline__ void glds16(const void* gsrc, unsigned lds_dst) { unsigned keep;
;     asm volatile("s_mov_b32 %0, m0\n\ts_mov_b32 m0, %2\n\ts_nop 0\n\tglobal_load_lds_dwordx4 %1, off\n\ts_mov_b32 m0, %0" : "=&s"(keep) : "v"(gsrc), "s"(lds_dst) : "memory"); }
; template <int KIND> __device__ __forceinline__ void attn_dma(unsigned dst, const bf16_t* src, const AttnUnit& u, int wid, int lane) {
;     const int np = u.nrows * 5;
;     const char* base = (const char*)(src + ((size_t)(u.b * NHEAD + u.h) * SEQ + u.krow_lo * 64 + 24 * u.jh) * HD);
; #pragma unroll
;     for (int it = 0; it < 10; ++it) {
;         const int pi = it * 8 + wid;
;         if (pi < np) {
;             const int w = (pi * 205) >> 10, p = pi - 5 * w, c = 8 * p + (lane >> 3);
;             const int sw = (KIND == 0) ? (((c >> 1) & 1) | (((c >> 3) & 3) << 1)) : ((((c >> 1) & 1) << 1) | (((c >> 3) & 1) << 2));
;             const int ch = (lane & 7) ^ sw;
;             const char* gp = base + (w * 64 + c) * (HD * 2) + ch * 16;
;             glds16(gp, (unsigned)__builtin_amdgcn_readfirstlane(dst + pi * 1024));
; __device__ __forceinline__ void p2_attention(Frame& F, const bf16_t* Qg, const bf16_t* Kg, const bf16_t* Vg, bf16_t* MIX) {
;     ...
;                 attn_dma<0>(lds0 + AT_A, Kg, un, wid, lane);
.Latt_done_nk5:
	s_mov_b32 m0, s11
	s_cmp_ge_i32 s66, s10
	s_cbranch_scc1 .LBB0_304
.LBB0_323:
	v_lshl_add_u64 v[0:1], s[8:9], 0, v[124:125]
	v_lshl_add_u64 v[0:1], v[0:1], 0, v[126:127]
	s_mov_b32 s11, m0
	s_mov_b32 m0, s67
	s_nop 0
	s_bitcmp1_b32 s101, 6
	s_cbranch_scc1 .Latt_def_nk6
	global_load_lds_dwordx4 v[0:1], off nt
	s_branch .Latt_done_nk6

; __device__ __forceinline__ void glds16(const void* gsrc, unsigned lds_dst) { unsigned keep;
;     asm volatile("s_mov_b32 %0, m0\n\ts_mov_b32 m0, %2\n\ts_nop 0\n\tglobal_load_lds_dwordx4 %1, off\n\ts_mov_b32 m0, %0" : "=&s"(keep) : "v"(gsrc), "s"(lds_dst) : "memory"); }
; template <int KIND> __device__ __forceinline__ void attn_dma(unsigned dst, const bf16_t* src, const AttnUnit& u, int wid, int lane) {
;     const int np = u.nrows * 5;
;     const char* base = (const char*)(src + ((size_t)(u.b * NHEAD + u.h) * SEQ + u.krow_lo * 64 + 24 * u.jh) * HD);
; #pragma unroll
;     for (int it = 0; it < 10; ++it) {
;         const int pi = it * 8 + wid;
;         if (pi < np) {
;             const int w = (pi * 205) >> 10, p = pi - 5 * w, c = 8 * p + (lane >> 3);
;             const int sw = (KIND == 0) ? (((c >> 1) & 1) | (((c >> 3) & 3) << 1)) : ((((c >> 1) & 1) << 1) | (((c >> 3) & 1) << 2));
;             const int ch = (lane & 7) ^ sw;
;             const char* gp = base + (w * 64 + c) * (HD * 2) + ch * 16;
;             glds16(gp, (unsigned)__builtin_amdgcn_readfirstlane(dst + pi * 1024));
; __device__ __forceinline__ void p2_attention(Frame& F, const bf16_t* Qg, const bf16_t* Kg, const bf16_t* Vg, bf16_t* MIX) {
;     ...
;                 attn_dma<0>(lds0 + AT_A, Kg, un, wid, lane);
.Latt_done_nk6:
	s_mov_b32 m0, s11
	s_cmp_ge_i32 s68, s10
	s_cbranch_scc1 .LBB0_305
.LBB0_324:
	v_lshl_add_u64 v[0:1], s[8:9], 0, v[128:129]
	v_lshl_add_u64 v[0:1], v[0:1], 0, v[130:131]
	s_mov_b32 s11, m0
	s_mov_b32 m0, s69
	s_nop 0
	s_bitcmp1_b32 s101, 7
	s_cbranch_scc1 .Latt_def_nk7
	global_load_lds_dwordx4 v[0:1], off nt
	s_branch .Latt_done_nk7

; __device__ __forceinline__ void glds16(const void* gsrc, unsigned lds_dst) { unsigned keep;
;     asm volatile("s_mov_b32 %0, m0\n\ts_mov_b32 m0, %2\n\ts_nop 0\n\tglobal_load_lds_dwordx4 %1, off\n\ts_mov_b32 m0, %0" : "=&s"(keep) : "v"(gsrc), "s"(lds_dst) : "memory"); }
; template <int KIND> __device__ __forceinline__ void attn_dma(unsigned dst, const bf16_t* src, const AttnUnit& u, int wid, int lane) {
;     const int np = u.nrows * 5;
;     const char* base = (const char*)(src + ((size_t)(u.b * NHEAD + u.h) * SEQ + u.krow_lo * 64 + 24 * u.jh) * HD);
; #pragma unroll
;     for (int it = 0; it < 10; ++it) {
;         const int pi = it * 8 + wid;
;         if (pi < np) {
;             const int w = (pi * 205) >> 10, p = pi - 5 * w, c = 8 * p + (lane >> 3);
;             const int sw = (KIND == 0) ? (((c >> 1) & 1) | (((c >> 3) & 3) << 1)) : ((((c >> 1) & 1) << 1) | (((c >> 3) & 1) << 2));
;             const int ch = (lane & 7) ^ sw;
;             const char* gp = base + (w * 64 + c) * (HD * 2) + ch * 16;
;             glds16(gp, (unsigned)__builtin_amdgcn_readfirstlane(dst + pi * 1024));
; __device__ __forceinline__ void p2_attention(Frame& F, const bf16_t* Qg, const bf16_t* Kg, const bf16_t* Vg, bf16_t* MIX) {
;     ...
;                 attn_dma<0>(lds0 + AT_A, Kg, un, wid, lane);
.Latt_done_nk7:
	s_mov_b32 m0, s11
	s_cmp_ge_i32 s70, s10
	s_cbranch_scc1 .LBB0_306
.LBB0_325:
	v_lshl_add_u64 v[0:1], s[8:9], 0, v[132:133]
	v_lshl_add_u64 v[0:1], v[0:1], 0, v[134:135]
	s_mov_b32 s11, m0
	s_mov_b32 m0, s71
	s_nop 0
	s_bitcmp1_b32 s101, 8
	s_cbranch_scc1 .Latt_def_nk8
	global_load_lds_dwordx4 v[0:1], off nt
	s_branch .Latt_done_nk8

; __device__ __forceinline__ void glds16(const void* gsrc, unsigned lds_dst) { unsigned keep;
;     asm volatile("s_mov_b32 %0, m0\n\ts_mov_b32 m0, %2\n\ts_nop 0\n\tglobal_load_lds_dwordx4 %1, off\n\ts_mov_b32 m0, %0" : "=&s"(keep) : "v"(gsrc), "s"(lds_dst) : "memory"); }
; template <int KIND> __device__ __forceinline__ void attn_dma(unsigned dst, const bf16_t* src, const AttnUnit& u, int wid, int lane) {
;     const int np = u.nrows * 5;
;     const char* base = (const char*)(src + ((size_t)(u.b * NHEAD + u.h) * SEQ + u.krow_lo * 64 + 24 * u.jh) * HD);
; #pragma unroll
;     for (int it = 0; it < 10; ++it) {
;         const int pi = it * 8 + wid;
;         if (pi < np) {
;             const int w = (pi * 205) >> 10, p = pi - 5 * w, c = 8 * p + (lane >> 3);
;             const int sw = (KIND == 0) ? (((c >> 1) & 1) | (((c >> 3) & 3) << 1)) : ((((c >> 1) & 1) << 1) | (((c >> 3) & 1) << 2));
;             const int ch = (lane & 7) ^ sw;
;             const char* gp = base + (w * 64 + c) * (HD * 2) + ch * 16;
;             glds16(gp, (unsigned)__builtin_amdgcn_readfirstlane(dst + pi * 1024));
; __device__ __forceinline__ void p2_attention(Frame& F, const bf16_t* Qg, const bf16_t* Kg, const bf16_t* Vg, bf16_t* MIX) {
;     ...
;                 attn_dma<0>(lds0 + AT_A, Kg, un, wid, lane);
.Latt_done_nk8:
	s_mov_b32 m0, s11
	s_cmp_ge_i32 s72, s10
	s_cbranch_scc1 .LBB0_283
.LBB0_326:
	v_lshl_add_u64 v[0:1], s[8:9], 0, v[136:137]
	v_lshl_add_u64 v[0:1], v[0:1], 0, v[138:139]
	s_mov_b32 s8, m0
	s_mov_b32 m0, s73
	s_nop 0
	s_bitcmp1_b32 s101, 9
	s_cbranch_scc1 .Latt_def_nk9
	global_load_lds_dwordx4 v[0:1], off nt
	s_branch .Latt_done_nk9

; __device__ __forceinline__ void glds16(const void* gsrc, unsigned lds_dst) { unsigned keep;
;     asm volatile("s_mov_b32 %0, m0\n\ts_mov_b32 m0, %2\n\ts_nop 0\n\tglobal_load_lds_dwordx4 %1, off\n\ts_mov_b32 m0, %0" : "=&s"(keep) : "v"(gsrc), "s"(lds_dst) : "memory"); }
; template <int KIND> __device__ __forceinline__ void attn_dma(unsigned dst, const bf16_t* src, const AttnUnit& u, int wid, int lane) {
;     const int np = u.nrows * 5;
;     const char* base = (const char*)(src + ((size_t)(u.b * NHEAD + u.h) * SEQ + u.krow_lo * 64 + 24 * u.jh) * HD);
; #pragma unroll
;     for (int it = 0; it < 10; ++it) {
;         const int pi = it * 8 + wid;
;         if (pi < np) {
;             const int w = (pi * 205) >> 10, p = pi - 5 * w, c = 8 * p + (lane >> 3);
;             const int sw = (KIND == 0) ? (((c >> 1) & 1) | (((c >> 3) & 3) << 1)) : ((((c >> 1) & 1) << 1) | (((c >> 3) & 1) << 2));
;             const int ch = (lane & 7) ^ sw;
;             const char* gp = base + (w * 64 + c) * (HD * 2) + ch * 16;
;             glds16(gp, (unsigned)__builtin_amdgcn_readfirstlane(dst + pi * 1024));
.Latt_done_nk9:
	s_mov_b32 m0, s8
	s_branch .LBB0_283
.LBB0_327:
	s_waitcnt vmcnt(5)
	v_lshl_add_u64 v[0:1], s[8:9], 0, v[100:101]
	v_lshl_add_u64 v[0:1], v[0:1], 0, v[102:103]
	s_mov_b32 s1, m0
	s_mov_b32 m0, s42
	s_nop 0
	s_bitcmp1_b32 s101, 0
	s_cbranch_scc1 .Latt_def_ik0
	global_load_lds_dwordx4 v[0:1], off nt
	s_branch .Latt_done_ik0

; __device__ __forceinline__ void glds16(const void* gsrc, unsigned lds_dst) { unsigned keep;
;     asm volatile("s_mov_b32 %0, m0\n\ts_mov_b32 m0, %2\n\ts_nop 0\n\tglobal_load_lds_dwordx4 %1, off\n\ts_mov_b32 m0, %0" : "=&s"(keep) : "v"(gsrc), "s"(lds_dst) : "memory"); }
; template <int KIND> __device__ __forceinline__ void attn_dma(unsigned dst, const bf16_t* src, const AttnUnit& u, int wid, int lane) {
;     const int np = u.nrows * 5;
;     const char* base = (const char*)(src + ((size_t)(u.b * NHEAD + u.h) * SEQ + u.krow_lo * 64 + 24 * u.jh) * HD);
; #pragma unroll
;     for (int it = 0; it < 10; ++it) {
;         const int pi = it * 8 + wid;
;         if (pi < np) {
;             const int w = (pi * 205) >> 10, p = pi - 5 * w, c = 8 * p + (lane >> 3);
;             const int sw = (KIND == 0) ? (((c >> 1) & 1) | (((c >> 3) & 3) << 1)) : ((((c >> 1) & 1) << 1) | (((c >> 3) & 1) << 2));
;             const int ch = (lane & 7) ^ sw;
;             const char* gp = base + (w * 64 + c) * (HD * 2) + ch * 16;
;             glds16(gp, (unsigned)__builtin_amdgcn_readfirstlane(dst + pi * 1024));
.Latt_done_ik0:
	s_mov_b32 m0, s1
	s_cmp_ge_i32 s43, s0
	s_cbranch_scc1 .LBB0_273
.LBB0_328:
	s_waitcnt vmcnt(5)
	v_lshl_add_u64 v[0:1], s[8:9], 0, v[104:105]
	v_lshl_add_u64 v[0:1], v[0:1], 0, v[106:107]
	s_mov_b32 s1, m0
	s_mov_b32 m0, s45
	s_nop 0
	s_bitcmp1_b32 s101, 1
	s_cbranch_scc1 .Latt_def_ik1
	global_load_lds_dwordx4 v[0:1], off nt
	s_branch .Latt_done_ik1

; __device__ __forceinline__ void glds16(const void* gsrc, unsigned lds_dst) { unsigned keep;
;     asm volatile("s_mov_b32 %0, m0\n\ts_mov_b32 m0, %2\n\ts_nop 0\n\tglobal_load_lds_dwordx4 %1, off\n\ts_mov_b32 m0, %0" : "=&s"(keep) : "v"(gsrc), "s"(lds_dst) : "memory"); }
; template <int KIND> __device__ __forceinline__ void attn_dma(unsigned dst, const bf16_t* src, const AttnUnit& u, int wid, int lane) {
;     const int np = u.nrows * 5;
;     const char* base = (const char*)(src + ((size_t)(u.b * NHEAD + u.h) * SEQ + u.krow_lo * 64 + 24 * u.jh) * HD);
; #pragma unroll
;     for (int it = 0; it < 10; ++it) {
;         const int pi = it * 8 + wid;
;         if (pi < np) {
;             const int w = (pi * 205) >> 10, p = pi - 5 * w, c = 8 * p + (lane >> 3);
;             const int sw = (KIND == 0) ? (((c >> 1) & 1) | (((c >> 3) & 3) << 1)) : ((((c >> 1) & 1) << 1) | (((c >> 3) & 1) << 2));
;             const int ch = (lane & 7) ^ sw;
;             const char* gp = base + (w * 64 + c) * (HD * 2) + ch * 16;
;             glds16(gp, (unsigned)__builtin_amdgcn_readfirstlane(dst + pi * 1024));
.Latt_done_ik1:
	s_mov_b32 m0, s1
	s_cmp_ge_i32 s48, s0
	s_cbranch_scc1 .LBB0_274
.LBB0_329:
	s_waitcnt vmcnt(5)
	v_lshl_add_u64 v[0:1], s[8:9], 0, v[108:109]
	v_lshl_add_u64 v[0:1], v[0:1], 0, v[110:111]
	s_mov_b32 s1, m0
	s_mov_b32 m0, s49
	s_nop 0
	s_bitcmp1_b32 s101, 2
	s_cbranch_scc1 .Latt_def_ik2
	global_load_lds_dwordx4 v[0:1], off nt
	s_branch .Latt_done_ik2

; __device__ __forceinline__ void glds16(const void* gsrc, unsigned lds_dst) { unsigned keep;
;     asm volatile("s_mov_b32 %0, m0\n\ts_mov_b32 m0, %2\n\ts_nop 0\n\tglobal_load_lds_dwordx4 %1, off\n\ts_mov_b32 m0, %0" : "=&s"(keep) : "v"(gsrc), "s"(lds_dst) : "memory"); }
; template <int KIND> __device__ __forceinline__ void attn_dma(unsigned dst, const bf16_t* src, const AttnUnit& u, int wid, int lane) {
;     const int np = u.nrows * 5;
;     const char* base = (const char*)(src + ((size_t)(u.b * NHEAD + u.h) * SEQ + u.krow_lo * 64 + 24 * u.jh) * HD);
; #pragma unroll
;     for (int it = 0; it < 10; ++it) {
;         const int pi = it * 8 + wid;
;         if (pi < np) {
;             const int w = (pi * 205) >> 10, p = pi - 5 * w, c = 8 * p + (lane >> 3);
;             const int sw = (KIND == 0) ? (((c >> 1) & 1) | (((c >> 3) & 3) << 1)) : ((((c >> 1) & 1) << 1) | (((c >> 3) & 1) << 2));
;             const int ch = (lane & 7) ^ sw;
;             const char* gp = base + (w * 64 + c) * (HD * 2) + ch * 16;
;             glds16(gp, (unsigned)__builtin_amdgcn_readfirstlane(dst + pi * 1024));
.Latt_done_ik2:
	s_mov_b32 m0, s1
	s_cmp_ge_i32 s50, s0
	s_cbranch_scc1 .LBB0_275
.LBB0_330:
	s_waitcnt vmcnt(5)
	v_lshl_add_u64 v[0:1], s[8:9], 0, v[112:113]
	v_lshl_add_u64 v[0:1], v[0:1], 0, v[114:115]
	s_mov_b32 s1, m0
	s_mov_b32 m0, s51
	s_nop 0
	s_bitcmp1_b32 s101, 3
	s_cbranch_scc1 .Latt_def_ik3
	global_load_lds_dwordx4 v[0:1], off nt
	s_branch .Latt_done_ik3

; __device__ __forceinline__ void glds16(const void* gsrc, unsigned lds_dst) { unsigned keep;
;     asm volatile("s_mov_b32 %0, m0\n\ts_mov_b32 m0, %2\n\ts_nop 0\n\tglobal_load_lds_dwordx4 %1, off\n\ts_mov_b32 m0, %0" : "=&s"(keep) : "v"(gsrc), "s"(lds_dst) : "memory"); }
; template <int KIND> __device__ __forceinline__ void attn_dma(unsigned dst, const bf16_t* src, const AttnUnit& u, int wid, int lane) {
;     const int np = u.nrows * 5;
;     const char* base = (const char*)(src + ((size_t)(u.b * NHEAD + u.h) * SEQ + u.krow_lo * 64 + 24 * u.jh) * HD);
; #pragma unroll
;     for (int it = 0; it < 10; ++it) {
;         const int pi = it * 8 + wid;
;         if (pi < np) {
;             const int w = (pi * 205) >> 10, p = pi - 5 * w, c = 8 * p + (lane >> 3);
;             const int sw = (KIND == 0) ? (((c >> 1) & 1) | (((c >> 3) & 3) << 1)) : ((((c >> 1) & 1) << 1) | (((c >> 3) & 1) << 2));
;             const int ch = (lane & 7) ^ sw;
;             const char* gp = base + (w * 64 + c) * (HD * 2) + ch * 16;
;             glds16(gp, (unsigned)__builtin_amdgcn_readfirstlane(dst + pi * 1024));
.Latt_done_ik3:
	s_mov_b32 m0, s1
	s_cmp_ge_i32 s54, s0
	s_cbranch_scc1 .LBB0_276
.LBB0_331:
	s_waitcnt vmcnt(5)
	v_lshl_add_u64 v[0:1], s[8:9], 0, v[116:117]
	v_lshl_add_u64 v[0:1], v[0:1], 0, v[118:119]
	s_mov_b32 s1, m0
	s_mov_b32 m0, s55
	s_nop 0
	s_bitcmp1_b32 s101, 4
	s_cbranch_scc1 .Latt_def_ik4
	global_load_lds_dwordx4 v[0:1], off nt
	s_branch .Latt_done_ik4

; __device__ __forceinline__ void glds16(const void* gsrc, unsigned lds_dst) { unsigned keep;
;     asm volatile("s_mov_b32 %0, m0\n\ts_mov_b32 m0, %2\n\ts_nop 0\n\tglobal_load_lds_dwordx4 %1, off\n\ts_mov_b32 m0, %0" : "=&s"(keep) : "v"(gsrc), "s"(lds_dst) : "memory"); }
; template <int KIND> __device__ __forceinline__ void attn_dma(unsigned dst, const bf16_t* src, const AttnUnit& u, int wid, int lane) {
;     const int np = u.nrows * 5;
;     const char* base = (const char*)(src + ((size_t)(u.b * NHEAD + u.h) * SEQ + u.krow_lo * 64 + 24 * u.jh) * HD);
; #pragma unroll
;     for (int it = 0; it < 10; ++it) {
;         const int pi = it * 8 + wid;
;         if (pi < np) {
;             const int w = (pi * 205) >> 10, p = pi - 5 * w, c = 8 * p + (lane >> 3);
;             const int sw = (KIND == 0) ? (((c >> 1) & 1) | (((c >> 3) & 3) << 1)) : ((((c >> 1) & 1) << 1) | (((c >> 3) & 1) << 2));
;             const int ch = (lane & 7) ^ sw;
;             const char* gp = base + (w * 64 + c) * (HD * 2) + ch * 16;
;             glds16(gp, (unsigned)__builtin_amdgcn_readfirstlane(dst + pi * 1024));
.Latt_done_ik4:
	s_mov_b32 m0, s1
	s_cmp_ge_i32 s64, s0
	s_cbranch_scc1 .LBB0_277
.LBB0_332:
	s_waitcnt vmcnt(5)
	v_lshl_add_u64 v[0:1], s[8:9], 0, v[120:121]
	v_lshl_add_u64 v[0:1], v[0:1], 0, v[122:123]
	s_mov_b32 s1, m0
	s_mov_b32 m0, s65
	s_nop 0
	s_bitcmp1_b32 s101, 5
	s_cbranch_scc1 .Latt_def_ik5
	global_load_lds_dwordx4 v[0:1], off nt
	s_branch .Latt_done_ik5

; __device__ __forceinline__ void glds16(const void* gsrc, unsigned lds_dst) { unsigned keep;
;     asm volatile("s_mov_b32 %0, m0\n\ts_mov_b32 m0, %2\n\ts_nop 0\n\tglobal_load_lds_dwordx4 %1, off\n\ts_mov_b32 m0, %0" : "=&s"(keep) : "v"(gsrc), "s"(lds_dst) : "memory"); }
; template <int KIND> __device__ __forceinline__ void attn_dma(unsigned dst, const bf16_t* src, const AttnUnit& u, int wid, int lane) {
;     const int np = u.nrows * 5;
;     const char* base = (const char*)(src + ((size_t)(u.b * NHEAD + u.h) * SEQ + u.krow_lo * 64 + 24 * u.jh) * HD);
; #pragma unroll
;     for (int it = 0; it < 10; ++it) {
;         const int pi = it * 8 + wid;
;         if (pi < np) {
;             const int w = (pi * 205) >> 10, p = pi - 5 * w, c = 8 * p + (lane >> 3);
;             const int sw = (KIND == 0) ? (((c >> 1) & 1) | (((c >> 3) & 3) << 1)) : ((((c >> 1) & 1) << 1) | (((c >> 3) & 1) << 2));
;             const int ch = (lane & 7) ^ sw;
;             const char* gp = base + (w * 64 + c) * (HD * 2) + ch * 16;
;             glds16(gp, (unsigned)__builtin_amdgcn_readfirstlane(dst + pi * 1024));
.Latt_done_ik5:
	s_mov_b32 m0, s1
	s_cmp_ge_i32 s66, s0
	s_cbranch_scc1 .LBB0_278
.LBB0_333:
	s_waitcnt vmcnt(5)
	v_lshl_add_u64 v[0:1], s[8:9], 0, v[124:125]
	v_lshl_add_u64 v[0:1], v[0:1], 0, v[126:127]
	s_mov_b32 s1, m0
	s_mov_b32 m0, s67
	s_nop 0
	s_bitcmp1_b32 s101, 6
	s_cbranch_scc1 .Latt_def_ik6
	global_load_lds_dwordx4 v[0:1], off nt
	s_branch .Latt_done_ik6

; __device__ __forceinline__ void glds16(const void* gsrc, unsigned lds_dst) { unsigned keep;
;     asm volatile("s_mov_b32 %0, m0\n\ts_mov_b32 m0, %2\n\ts_nop 0\n\tglobal_load_lds_dwordx4 %1, off\n\ts_mov_b32 m0, %0" : "=&s"(keep) : "v"(gsrc), "s"(lds_dst) : "memory"); }
; template <int KIND> __device__ __forceinline__ void attn_dma(unsigned dst, const bf16_t* src, const AttnUnit& u, int wid, int lane) {
;     const int np = u.nrows * 5;
;     const char* base = (const char*)(src + ((size_t)(u.b * NHEAD + u.h) * SEQ + u.krow_lo * 64 + 24 * u.jh) * HD);
; #pragma unroll
;     for (int it = 0; it < 10; ++it) {
;         const int pi = it * 8 + wid;
;         if (pi < np) {
;             const int w = (pi * 205) >> 10, p = pi - 5 * w, c = 8 * p + (lane >> 3);
;             const int sw = (KIND == 0) ? (((c >> 1) & 1) | (((c >> 3) & 3) << 1)) : ((((c >> 1) & 1) << 1) | (((c >> 3) & 1) << 2));
;             const int ch = (lane & 7) ^ sw;
;             const char* gp = base + (w * 64 + c) * (HD * 2) + ch * 16;
;             glds16(gp, (unsigned)__builtin_amdgcn_readfirstlane(dst + pi * 1024));
.Latt_done_ik6:
	s_mov_b32 m0, s1
	s_cmp_ge_i32 s68, s0
	s_cbranch_scc1 .LBB0_279
.LBB0_334:
	s_waitcnt vmcnt(5)
	v_lshl_add_u64 v[0:1], s[8:9], 0, v[128:129]
	v_lshl_add_u64 v[0:1], v[0:1], 0, v[130:131]
	s_mov_b32 s1, m0
	s_mov_b32 m0, s69
	s_nop 0
	s_bitcmp1_b32 s101, 7
	s_cbranch_scc1 .Latt_def_ik7
	global_load_lds_dwordx4 v[0:1], off nt
	s_branch .Latt_done_ik7

; __device__ __forceinline__ void glds16(const void* gsrc, unsigned lds_dst) { unsigned keep;
;     asm volatile("s_mov_b32 %0, m0\n\ts_mov_b32 m0, %2\n\ts_nop 0\n\tglobal_load_lds_dwordx4 %1, off\n\ts_mov_b32 m0, %0" : "=&s"(keep) : "v"(gsrc), "s"(lds_dst) : "memory"); }
; template <int KIND> __device__ __forceinline__ void attn_dma(unsigned dst, const bf16_t* src, const AttnUnit& u, int wid, int lane) {
;     const int np = u.nrows * 5;
;     const char* base = (const char*)(src + ((size_t)(u.b * NHEAD + u.h) * SEQ + u.krow_lo * 64 + 24 * u.jh) * HD);
; #pragma unroll
;     for (int it = 0; it < 10; ++it) {
;         const int pi = it * 8 + wid;
;         if (pi < np) {
;             const int w = (pi * 205) >> 10, p = pi - 5 * w, c = 8 * p + (lane >> 3);
;             const int sw = (KIND == 0) ? (((c >> 1) & 1) | (((c >> 3) & 3) << 1)) : ((((c >> 1) & 1) << 1) | (((c >> 3) & 1) << 2));
;             const int ch = (lane & 7) ^ sw;
;             const char* gp = base + (w * 64 + c) * (HD * 2) + ch * 16;
;             glds16(gp, (unsigned)__builtin_amdgcn_readfirstlane(dst + pi * 1024));
.Latt_done_ik7:
	s_mov_b32 m0, s1
	s_cmp_ge_i32 s70, s0
	s_cbranch_scc1 .LBB0_280
.LBB0_335:
	s_waitcnt vmcnt(5)
	v_lshl_add_u64 v[0:1], s[8:9], 0, v[132:133]
	v_lshl_add_u64 v[0:1], v[0:1], 0, v[134:135]
	s_mov_b32 s1, m0
	s_mov_b32 m0, s71
	s_nop 0
	s_bitcmp1_b32 s101, 8
	s_cbranch_scc1 .Latt_def_ik8
	global_load_lds_dwordx4 v[0:1], off nt
	s_branch .Latt_done_ik8

; __device__ __forceinline__ void glds16(const void* gsrc, unsigned lds_dst) { unsigned keep;
;     asm volatile("s_mov_b32 %0, m0\n\ts_mov_b32 m0, %2\n\ts_nop 0\n\tglobal_load_lds_dwordx4 %1, off\n\ts_mov_b32 m0, %0" : "=&s"(keep) : "v"(gsrc), "s"(lds_dst) : "memory"); }
; template <int KIND> __device__ __forceinline__ void attn_dma(unsigned dst, const bf16_t* src, const AttnUnit& u, int wid, int lane) {
;     const int np = u.nrows * 5;
;     const char* base = (const char*)(src + ((size_t)(u.b * NHEAD + u.h) * SEQ + u.krow_lo * 64 + 24 * u.jh) * HD);
; #pragma unroll
;     for (int it = 0; it < 10; ++it) {
;         const int pi = it * 8 + wid;
;         if (pi < np) {
;             const int w = (pi * 205) >> 10, p = pi - 5 * w, c = 8 * p + (lane >> 3);
;             const int sw = (KIND == 0) ? (((c >> 1) & 1) | (((c >> 3) & 3) << 1)) : ((((c >> 1) & 1) << 1) | (((c >> 3) & 1) << 2));
;             const int ch = (lane & 7) ^ sw;
;             const char* gp = base + (w * 64 + c) * (HD * 2) + ch * 16;
;             glds16(gp, (unsigned)__builtin_amdgcn_readfirstlane(dst + pi * 1024));
.Latt_done_ik8:
	s_mov_b32 m0, s1
	s_cmp_ge_i32 s72, s0
	s_cbranch_scc0 .LBB0_281
	s_branch .LBB0_282

; __global__ void __launch_bounds__(NWAVES * 64, 2) fwd_megakernel(Args args) {
;     extern __shared__ __attribute__((aligned(16))) unsigned char lds[];
	.amdhsa_kernel _Z14fwd_megakernel4Args
		.amdhsa_group_segment_fixed_size 0
		.amdhsa_private_segment_fixed_size 0
		.amdhsa_kernarg_size 392
		.amdhsa_user_sgpr_count 2
		.amdhsa_user_sgpr_dispatch_ptr 0
		.amdhsa_user_sgpr_queue_ptr 0
		.amdhsa_user_sgpr_kernarg_segment_ptr 1
		.amdhsa_user_sgpr_dispatch_id 0
		.amdhsa_user_sgpr_kernarg_preload_length 0
		.amdhsa_user_sgpr_kernarg_preload_offset 0
		.amdhsa_user_sgpr_private_segment_size 0
		.amdhsa_uses_dynamic_stack 0
		.amdhsa_enable_private_segment 0
		.amdhsa_system_sgpr_workgroup_id_x 1
		.amdhsa_system_sgpr_workgroup_id_y 0
		.amdhsa_system_sgpr_workgroup_id_z 0
		.amdhsa_system_sgpr_workgroup_info 0
		.amdhsa_system_vgpr_workitem_id 0
		.amdhsa_next_free_vgpr 253
		.amdhsa_next_free_sgpr 102
		.amdhsa_accum_offset 256
		.amdhsa_reserve_vcc 1
		.amdhsa_float_round_mode_32 0
		.amdhsa_float_round_mode_16_64 0
		.amdhsa_float_denorm_mode_32 3
		.amdhsa_float_denorm_mode_16_64 3
		.amdhsa_dx10_clamp 1
		.amdhsa_ieee_mode 1
		.amdhsa_fp16_overflow 0
		.amdhsa_tg_split 0
		.amdhsa_exception_fp_ieee_invalid_op 0
		.amdhsa_exception_fp_denorm_src 0
		.amdhsa_exception_fp_ieee_div_zero 0
		.amdhsa_exception_fp_ieee_overflow 0
		.amdhsa_exception_fp_ieee_underflow 0
		.amdhsa_exception_fp_ieee_inexact 0
		.amdhsa_exception_int_div_zero 0
	.end_amdhsa_kernel

; __global__ void __launch_bounds__(NWAVES * 64, 2) fwd_megakernel(Args args) {
amdhsa.kernels:
  - .agpr_count:     0
    .args:
      - .offset:         0
        .size:           136
        .value_kind:     by_value
      - .offset:         136
        .size:           4
        .value_kind:     hidden_block_count_x
      - .offset:         140
        .size:           4
        .value_kind:     hidden_block_count_y
      - .offset:         144
        .size:           4
        .value_kind:     hidden_block_count_z
      - .offset:         148
        .size:           2
        .value_kind:     hidden_group_size_x
      - .offset:         150
        .size:           2
        .value_kind:     hidden_group_size_y
      - .offset:         152
        .size:           2
        .value_kind:     hidden_group_size_z
      - .offset:         154
        .size:           2
        .value_kind:     hidden_remainder_x
      - .offset:         156
        .size:           2
        .value_kind:     hidden_remainder_y
      - .offset:         158
        .size:           2
        .value_kind:     hidden_remainder_z
      - .offset:         176
        .size:           8
        .value_kind:     hidden_global_offset_x
      - .offset:         184
        .size:           8
        .value_kind:     hidden_global_offset_y
      - .offset:         192
        .size:           8
        .value_kind:     hidden_global_offset_z
      - .offset:         200
        .size:           2
        .value_kind:     hidden_grid_dims
      - .offset:         256
        .size:           4
        .value_kind:     hidden_dynamic_lds_size
    .group_segment_fixed_size: 0
    .kernarg_segment_align: 8
    .kernarg_segment_size: 392
    .language:       OpenCL C
    .language_version:
      - 2
      - 0
    .max_flat_workgroup_size: 512
    .name:           _Z14fwd_megakernel4Args
    .private_segment_fixed_size: 0
    .sgpr_count:     108
    .sgpr_spill_count: 4
    .symbol:         _Z14fwd_megakernel4Args.kd
    .uniform_work_group_size: 1
    .uses_dynamic_stack: false
    .vgpr_count:     253
    .vgpr_spill_count: 0
    .wavefront_size: 64
